# ping-pong K-loops: priority drop moved behind the barrier at MFMA-segment ends; vmcnt+lgkmcnt waits merged
# baseline (speedup 1.0000x reference)
.LBB0_288:
	s_ashr_i32 s53, s52, 31
	s_lshl_b64 s[54:55], s[52:53], 19
	s_add_u32 s54, s66, s54
	s_addc_u32 s55, s67, s55
	s_and_b64 s[56:57], s[40:41], exec
	s_cselect_b32 s53, s55, s61
	s_cselect_b32 s80, s54, s60
	s_ashr_i32 s43, s42, 31
	s_lshl_b64 s[56:57], s[42:43], 19
	s_add_u32 s56, s68, s56
	s_addc_u32 s57, s69, s57
	s_and_b64 s[62:63], s[40:41], exec
	s_cselect_b32 s43, s57, s59
	s_cselect_b32 s81, s56, s58
	s_add_u32 s82, s58, 0x100
	s_addc_u32 s83, s59, 0
	s_add_u32 s58, s60, 0x40080
	s_addc_u32 s59, s61, 0
	s_mov_b32 s84, -2
	s_add_u32 s60, s58, 0xfffc0080
	s_addc_u32 s61, s59, -1
	s_add_i32 s85, 0, 0x10000
	s_cmp_eq_u32 s84, 12
	s_cselect_b32 s63, s53, s61
	s_cselect_b32 s62, s80, s60
	v_add_u32_e32 v140, s85, v142
	s_cselect_b32 s61, s43, s83
	s_cselect_b32 s60, s81, s82
	s_add_i32 s90, 0, 0x14000
	ds_read_b128 v[156:159], v140
	ds_read_b128 v[160:163], v140 offset:1024
	ds_read_b128 v[164:167], v140 offset:2048
	ds_read_b128 v[168:171], v140 offset:3072
	v_add_u32_e32 v140, s90, v142
	ds_read_b128 v[172:175], v140
	ds_read_b128 v[176:179], v140 offset:1024
	ds_read_b128 v[180:183], v140 offset:2048
	ds_read_b128 v[184:187], v140 offset:3072
	v_lshl_add_u64 v[140:141], s[58:59], 0, v[138:139]
	s_add_i32 m0, s71, 0xc000
	ds_read_b128 v[188:191], v144
	ds_read_b128 v[192:195], v144 offset:1024
	ds_read_b128 v[196:199], v144 offset:2048
	ds_read_b128 v[200:203], v144 offset:3072
	ds_read_b128 v[204:207], v144 offset:4096
	ds_read_b128 v[218:221], v144 offset:5120
	ds_read_b128 v[222:225], v144 offset:6144
	ds_read_b128 v[226:229], v144 offset:7168
	global_load_lds_dwordx4 v[140:141], off
	v_lshl_add_u64 v[140:141], s[58:59], 0, v[136:137]
	s_add_i32 m0, s71, 0xe000
	s_nop 0
	global_load_lds_dwordx4 v[140:141], off
	s_waitcnt vmcnt(8) lgkmcnt(0)
	s_setprio 1
	s_barrier
	v_mfma_f32_16x16x32_bf16 v[124:127], v[156:159], v[188:191], 0
	v_mfma_f32_16x16x32_bf16 v[120:123], v[164:167], v[188:191], 0
	v_mfma_f32_16x16x32_bf16 v[112:115], v[156:159], v[196:199], 0
	v_mfma_f32_16x16x32_bf16 v[104:107], v[164:167], v[196:199], 0
	v_mfma_f32_16x16x32_bf16 v[96:99], v[156:159], v[204:207], 0
	v_mfma_f32_16x16x32_bf16 v[88:91], v[164:167], v[204:207], 0
	v_mfma_f32_16x16x32_bf16 v[80:83], v[156:159], v[222:225], 0
	v_mfma_f32_16x16x32_bf16 v[72:75], v[164:167], v[222:225], 0
	v_mfma_f32_16x16x32_bf16 v[124:127], v[160:163], v[192:195], v[124:127]
	v_mfma_f32_16x16x32_bf16 v[120:123], v[168:171], v[192:195], v[120:123]
	v_mfma_f32_16x16x32_bf16 v[112:115], v[160:163], v[200:203], v[112:115]
	v_mfma_f32_16x16x32_bf16 v[104:107], v[168:171], v[200:203], v[104:107]
	v_mfma_f32_16x16x32_bf16 v[96:99], v[160:163], v[218:221], v[96:99]
	v_mfma_f32_16x16x32_bf16 v[88:91], v[168:171], v[218:221], v[88:91]
	v_mfma_f32_16x16x32_bf16 v[80:83], v[160:163], v[226:229], v[80:83]
	v_mfma_f32_16x16x32_bf16 v[72:75], v[168:171], v[226:229], v[72:75]
	s_setprio 0
	s_setprio 1
	v_mfma_f32_16x16x32_bf16 v[116:119], v[172:175], v[188:191], 0
	v_mfma_f32_16x16x32_bf16 v[108:111], v[180:183], v[188:191], 0
	v_mfma_f32_16x16x32_bf16 v[100:103], v[172:175], v[196:199], 0
	v_mfma_f32_16x16x32_bf16 v[92:95], v[180:183], v[196:199], 0
	v_mfma_f32_16x16x32_bf16 v[84:87], v[172:175], v[204:207], 0
	v_mfma_f32_16x16x32_bf16 v[76:79], v[180:183], v[204:207], 0
	v_mfma_f32_16x16x32_bf16 v[68:71], v[172:175], v[222:225], 0
	v_mfma_f32_16x16x32_bf16 v[64:67], v[180:183], v[222:225], 0
	v_mfma_f32_16x16x32_bf16 v[116:119], v[176:179], v[192:195], v[116:119]
	v_mfma_f32_16x16x32_bf16 v[108:111], v[184:187], v[192:195], v[108:111]
	v_mfma_f32_16x16x32_bf16 v[100:103], v[176:179], v[200:203], v[100:103]
	v_mfma_f32_16x16x32_bf16 v[92:95], v[184:187], v[200:203], v[92:95]
	v_mfma_f32_16x16x32_bf16 v[84:87], v[176:179], v[218:221], v[84:87]
	v_mfma_f32_16x16x32_bf16 v[76:79], v[184:187], v[218:221], v[76:79]
	v_mfma_f32_16x16x32_bf16 v[68:71], v[176:179], v[226:229], v[68:71]
	v_mfma_f32_16x16x32_bf16 v[64:67], v[184:187], v[226:229], v[64:67]
	s_barrier
	s_setprio 0
	s_add_i32 s85, s85, s70
	v_lshl_add_u64 v[140:141], s[60:61], 0, v[148:149]
	s_mov_b32 m0, s85
	ds_read_b128 v[188:191], v144 offset:16384
	ds_read_b128 v[192:195], v144 offset:17408
	ds_read_b128 v[196:199], v144 offset:18432
	ds_read_b128 v[200:203], v144 offset:19456
	ds_read_b128 v[204:207], v144 offset:20480
	ds_read_b128 v[218:221], v144 offset:21504
	ds_read_b128 v[222:225], v144 offset:22528
	ds_read_b128 v[226:229], v144 offset:23552
	global_load_lds_dwordx4 v[140:141], off
	s_add_i32 m0, s85, 0x2000
	s_add_u32 s88, s60, 0x40000
	v_lshl_add_u64 v[146:147], s[60:61], 0, v[130:131]
	s_addc_u32 s89, s61, 0
	s_add_i32 s85, s90, s70
	global_load_lds_dwordx4 v[146:147], off
	v_lshl_add_u64 v[208:209], s[88:89], 0, v[148:149]
	s_mov_b32 m0, s85
	v_lshl_add_u64 v[212:213], s[62:63], 0, v[132:133]
	global_load_lds_dwordx4 v[208:209], off
	v_lshl_add_u64 v[208:209], s[88:89], 0, v[130:131]
	s_add_i32 m0, s85, 0x2000
	s_nop 0
	global_load_lds_dwordx4 v[208:209], off
	v_lshl_add_u64 v[208:209], s[62:63], 0, v[134:135]
	s_mov_b32 m0, s71
	s_nop 0
	global_load_lds_dwordx4 v[208:209], off
	s_mov_b32 m0, s72
	s_nop 0
	global_load_lds_dwordx4 v[212:213], off
	s_waitcnt vmcnt(8) lgkmcnt(0)
	s_setprio 1
	s_barrier
	v_mfma_f32_16x16x32_bf16 v[60:63], v[156:159], v[188:191], 0
	v_mfma_f32_16x16x32_bf16 v[56:59], v[164:167], v[188:191], 0
	v_mfma_f32_16x16x32_bf16 v[48:51], v[156:159], v[196:199], 0
	v_mfma_f32_16x16x32_bf16 v[40:43], v[164:167], v[196:199], 0
	v_mfma_f32_16x16x32_bf16 v[32:35], v[156:159], v[204:207], 0
	v_mfma_f32_16x16x32_bf16 v[24:27], v[164:167], v[204:207], 0
	v_mfma_f32_16x16x32_bf16 v[16:19], v[156:159], v[222:225], 0
	v_mfma_f32_16x16x32_bf16 v[8:11], v[164:167], v[222:225], 0
	v_mfma_f32_16x16x32_bf16 v[60:63], v[160:163], v[192:195], v[60:63]
	v_mfma_f32_16x16x32_bf16 v[56:59], v[168:171], v[192:195], v[56:59]
	v_mfma_f32_16x16x32_bf16 v[48:51], v[160:163], v[200:203], v[48:51]
	v_mfma_f32_16x16x32_bf16 v[40:43], v[168:171], v[200:203], v[40:43]
	v_mfma_f32_16x16x32_bf16 v[32:35], v[160:163], v[218:221], v[32:35]
	v_mfma_f32_16x16x32_bf16 v[24:27], v[168:171], v[218:221], v[24:27]
	v_mfma_f32_16x16x32_bf16 v[16:19], v[160:163], v[226:229], v[16:19]
	v_mfma_f32_16x16x32_bf16 v[8:11], v[168:171], v[226:229], v[8:11]
	s_setprio 0
	s_setprio 1
	v_mfma_f32_16x16x32_bf16 v[52:55], v[172:175], v[188:191], 0
	v_mfma_f32_16x16x32_bf16 v[44:47], v[180:183], v[188:191], 0
	v_mfma_f32_16x16x32_bf16 v[36:39], v[172:175], v[196:199], 0
	v_mfma_f32_16x16x32_bf16 v[28:31], v[180:183], v[196:199], 0
	v_mfma_f32_16x16x32_bf16 v[20:23], v[172:175], v[204:207], 0
	v_mfma_f32_16x16x32_bf16 v[12:15], v[180:183], v[204:207], 0
	v_mfma_f32_16x16x32_bf16 v[4:7], v[172:175], v[222:225], 0
	v_mfma_f32_16x16x32_bf16 v[0:3], v[180:183], v[222:225], 0
	v_mfma_f32_16x16x32_bf16 v[52:55], v[176:179], v[192:195], v[52:55]
	v_mfma_f32_16x16x32_bf16 v[44:47], v[184:187], v[192:195], v[44:47]
	v_mfma_f32_16x16x32_bf16 v[36:39], v[176:179], v[200:203], v[36:39]
	v_mfma_f32_16x16x32_bf16 v[28:31], v[184:187], v[200:203], v[28:31]
	v_mfma_f32_16x16x32_bf16 v[20:23], v[176:179], v[218:221], v[20:23]
	v_mfma_f32_16x16x32_bf16 v[12:15], v[184:187], v[218:221], v[12:15]
	v_mfma_f32_16x16x32_bf16 v[4:7], v[176:179], v[226:229], v[4:7]
	v_mfma_f32_16x16x32_bf16 v[0:3], v[184:187], v[226:229], v[0:3]
	s_barrier
	s_setprio 0
	s_branch .Lg1_p3
	.p2align 6
	.fill 12, 4, 0xBF800000
.LBB0_289:
	s_add_u32 s60, s58, 0xfffc0080
	s_addc_u32 s61, s59, -1
	s_add_i32 s85, 0, 0x10000
	s_cmp_eq_u32 s84, 12
	s_cselect_b32 s63, s53, s61
	s_cselect_b32 s62, s80, s60
	v_add_u32_e32 v140, s85, v142
	s_cselect_b32 s61, s43, s83
	s_cselect_b32 s60, s81, s82
	s_add_i32 s90, 0, 0x14000
	ds_read_b128 v[156:159], v140
	ds_read_b128 v[160:163], v140 offset:1024
	ds_read_b128 v[164:167], v140 offset:2048
	ds_read_b128 v[168:171], v140 offset:3072
	v_add_u32_e32 v140, s90, v142
	ds_read_b128 v[172:175], v140
	ds_read_b128 v[176:179], v140 offset:1024
	ds_read_b128 v[180:183], v140 offset:2048
	ds_read_b128 v[184:187], v140 offset:3072
	v_lshl_add_u64 v[140:141], s[58:59], 0, v[138:139]
	s_add_i32 m0, s71, 0xc000
	ds_read_b128 v[188:191], v144
	ds_read_b128 v[192:195], v144 offset:1024
	ds_read_b128 v[196:199], v144 offset:2048
	ds_read_b128 v[200:203], v144 offset:3072
	ds_read_b128 v[204:207], v144 offset:4096
	ds_read_b128 v[218:221], v144 offset:5120
	ds_read_b128 v[222:225], v144 offset:6144
	ds_read_b128 v[226:229], v144 offset:7168
	global_load_lds_dwordx4 v[140:141], off
	v_lshl_add_u64 v[140:141], s[58:59], 0, v[136:137]
	s_add_i32 m0, s71, 0xe000
	s_nop 0
	global_load_lds_dwordx4 v[140:141], off
	s_waitcnt vmcnt(8) lgkmcnt(0)
	s_setprio 1
	s_barrier
	v_mfma_f32_16x16x32_bf16 v[124:127], v[156:159], v[188:191], v[124:127]
	v_mfma_f32_16x16x32_bf16 v[120:123], v[164:167], v[188:191], v[120:123]
	v_mfma_f32_16x16x32_bf16 v[112:115], v[156:159], v[196:199], v[112:115]
	v_mfma_f32_16x16x32_bf16 v[104:107], v[164:167], v[196:199], v[104:107]
	v_mfma_f32_16x16x32_bf16 v[96:99], v[156:159], v[204:207], v[96:99]
	v_mfma_f32_16x16x32_bf16 v[88:91], v[164:167], v[204:207], v[88:91]
	v_mfma_f32_16x16x32_bf16 v[80:83], v[156:159], v[222:225], v[80:83]
	v_mfma_f32_16x16x32_bf16 v[72:75], v[164:167], v[222:225], v[72:75]
	v_mfma_f32_16x16x32_bf16 v[124:127], v[160:163], v[192:195], v[124:127]
	v_mfma_f32_16x16x32_bf16 v[120:123], v[168:171], v[192:195], v[120:123]
	v_mfma_f32_16x16x32_bf16 v[112:115], v[160:163], v[200:203], v[112:115]
	v_mfma_f32_16x16x32_bf16 v[104:107], v[168:171], v[200:203], v[104:107]
	v_mfma_f32_16x16x32_bf16 v[96:99], v[160:163], v[218:221], v[96:99]
	v_mfma_f32_16x16x32_bf16 v[88:91], v[168:171], v[218:221], v[88:91]
	v_mfma_f32_16x16x32_bf16 v[80:83], v[160:163], v[226:229], v[80:83]
	v_mfma_f32_16x16x32_bf16 v[72:75], v[168:171], v[226:229], v[72:75]
	s_setprio 0
	s_setprio 1
	v_mfma_f32_16x16x32_bf16 v[116:119], v[172:175], v[188:191], v[116:119]
	v_mfma_f32_16x16x32_bf16 v[108:111], v[180:183], v[188:191], v[108:111]
	v_mfma_f32_16x16x32_bf16 v[100:103], v[172:175], v[196:199], v[100:103]
	v_mfma_f32_16x16x32_bf16 v[92:95], v[180:183], v[196:199], v[92:95]
	v_mfma_f32_16x16x32_bf16 v[84:87], v[172:175], v[204:207], v[84:87]
	v_mfma_f32_16x16x32_bf16 v[76:79], v[180:183], v[204:207], v[76:79]
	v_mfma_f32_16x16x32_bf16 v[68:71], v[172:175], v[222:225], v[68:71]
	v_mfma_f32_16x16x32_bf16 v[64:67], v[180:183], v[222:225], v[64:67]
	v_mfma_f32_16x16x32_bf16 v[116:119], v[176:179], v[192:195], v[116:119]
	v_mfma_f32_16x16x32_bf16 v[108:111], v[184:187], v[192:195], v[108:111]
	v_mfma_f32_16x16x32_bf16 v[100:103], v[176:179], v[200:203], v[100:103]
	v_mfma_f32_16x16x32_bf16 v[92:95], v[184:187], v[200:203], v[92:95]
	v_mfma_f32_16x16x32_bf16 v[84:87], v[176:179], v[218:221], v[84:87]
	v_mfma_f32_16x16x32_bf16 v[76:79], v[184:187], v[218:221], v[76:79]
	v_mfma_f32_16x16x32_bf16 v[68:71], v[176:179], v[226:229], v[68:71]
	v_mfma_f32_16x16x32_bf16 v[64:67], v[184:187], v[226:229], v[64:67]
	s_barrier
	s_setprio 0
	s_add_i32 s85, s85, s70
	v_lshl_add_u64 v[140:141], s[60:61], 0, v[148:149]
	s_mov_b32 m0, s85
	ds_read_b128 v[188:191], v144 offset:16384
	ds_read_b128 v[192:195], v144 offset:17408
	ds_read_b128 v[196:199], v144 offset:18432
	ds_read_b128 v[200:203], v144 offset:19456
	ds_read_b128 v[204:207], v144 offset:20480
	ds_read_b128 v[218:221], v144 offset:21504
	ds_read_b128 v[222:225], v144 offset:22528
	ds_read_b128 v[226:229], v144 offset:23552
	global_load_lds_dwordx4 v[140:141], off
	s_add_i32 m0, s85, 0x2000
	s_add_u32 s88, s60, 0x40000
	v_lshl_add_u64 v[146:147], s[60:61], 0, v[130:131]
	s_addc_u32 s89, s61, 0
	s_add_i32 s85, s90, s70
	global_load_lds_dwordx4 v[146:147], off
	v_lshl_add_u64 v[208:209], s[88:89], 0, v[148:149]
	s_mov_b32 m0, s85
	v_lshl_add_u64 v[212:213], s[62:63], 0, v[132:133]
	global_load_lds_dwordx4 v[208:209], off
	v_lshl_add_u64 v[208:209], s[88:89], 0, v[130:131]
	s_add_i32 m0, s85, 0x2000
	s_nop 0
	global_load_lds_dwordx4 v[208:209], off
	v_lshl_add_u64 v[208:209], s[62:63], 0, v[134:135]
	s_mov_b32 m0, s71
	s_nop 0
	global_load_lds_dwordx4 v[208:209], off
	s_mov_b32 m0, s72
	s_nop 0
	global_load_lds_dwordx4 v[212:213], off
	s_waitcnt vmcnt(8) lgkmcnt(0)
	s_setprio 1
	s_barrier
	v_mfma_f32_16x16x32_bf16 v[60:63], v[156:159], v[188:191], v[60:63]
	v_mfma_f32_16x16x32_bf16 v[56:59], v[164:167], v[188:191], v[56:59]
	v_mfma_f32_16x16x32_bf16 v[48:51], v[156:159], v[196:199], v[48:51]
	v_mfma_f32_16x16x32_bf16 v[40:43], v[164:167], v[196:199], v[40:43]
	v_mfma_f32_16x16x32_bf16 v[32:35], v[156:159], v[204:207], v[32:35]
	v_mfma_f32_16x16x32_bf16 v[24:27], v[164:167], v[204:207], v[24:27]
	v_mfma_f32_16x16x32_bf16 v[16:19], v[156:159], v[222:225], v[16:19]
	v_mfma_f32_16x16x32_bf16 v[8:11], v[164:167], v[222:225], v[8:11]
	v_mfma_f32_16x16x32_bf16 v[60:63], v[160:163], v[192:195], v[60:63]
	v_mfma_f32_16x16x32_bf16 v[56:59], v[168:171], v[192:195], v[56:59]
	v_mfma_f32_16x16x32_bf16 v[48:51], v[160:163], v[200:203], v[48:51]
	v_mfma_f32_16x16x32_bf16 v[40:43], v[168:171], v[200:203], v[40:43]
	v_mfma_f32_16x16x32_bf16 v[32:35], v[160:163], v[218:221], v[32:35]
	v_mfma_f32_16x16x32_bf16 v[24:27], v[168:171], v[218:221], v[24:27]
	v_mfma_f32_16x16x32_bf16 v[16:19], v[160:163], v[226:229], v[16:19]
	v_mfma_f32_16x16x32_bf16 v[8:11], v[168:171], v[226:229], v[8:11]
	s_setprio 0
	s_setprio 1
	v_mfma_f32_16x16x32_bf16 v[52:55], v[172:175], v[188:191], v[52:55]
	v_mfma_f32_16x16x32_bf16 v[44:47], v[180:183], v[188:191], v[44:47]
	v_mfma_f32_16x16x32_bf16 v[36:39], v[172:175], v[196:199], v[36:39]
	v_mfma_f32_16x16x32_bf16 v[28:31], v[180:183], v[196:199], v[28:31]
	v_mfma_f32_16x16x32_bf16 v[20:23], v[172:175], v[204:207], v[20:23]
	v_mfma_f32_16x16x32_bf16 v[12:15], v[180:183], v[204:207], v[12:15]
	v_mfma_f32_16x16x32_bf16 v[4:7], v[172:175], v[222:225], v[4:7]
	v_mfma_f32_16x16x32_bf16 v[0:3], v[180:183], v[222:225], v[0:3]
	v_mfma_f32_16x16x32_bf16 v[52:55], v[176:179], v[192:195], v[52:55]
	v_mfma_f32_16x16x32_bf16 v[44:47], v[184:187], v[192:195], v[44:47]
	v_mfma_f32_16x16x32_bf16 v[36:39], v[176:179], v[200:203], v[36:39]
	v_mfma_f32_16x16x32_bf16 v[28:31], v[184:187], v[200:203], v[28:31]
	v_mfma_f32_16x16x32_bf16 v[20:23], v[176:179], v[218:221], v[20:23]
	v_mfma_f32_16x16x32_bf16 v[12:15], v[184:187], v[218:221], v[12:15]
	v_mfma_f32_16x16x32_bf16 v[4:7], v[176:179], v[226:229], v[4:7]
	v_mfma_f32_16x16x32_bf16 v[0:3], v[184:187], v[226:229], v[0:3]
	s_barrier
	s_setprio 0
.Lg1_p3:
	s_add_i32 s85, 0, 0x18000
	v_add_u32_e32 v145, s85, v142
	s_add_i32 s88, 0, 0x1c000
	ds_read_b128 v[156:159], v145
	ds_read_b128 v[160:163], v145 offset:1024
	ds_read_b128 v[164:167], v145 offset:2048
	ds_read_b128 v[168:171], v145 offset:3072
	v_add_u32_e32 v145, s88, v142
	ds_read_b128 v[172:175], v145
	ds_read_b128 v[176:179], v145 offset:1024
	ds_read_b128 v[180:183], v145 offset:2048
	ds_read_b128 v[184:187], v145 offset:3072
	s_add_u32 s62, s62, 0x40000
	s_addc_u32 s63, s63, 0
	s_mov_b32 m0, s73
	v_lshl_add_u64 v[230:231], s[62:63], 0, v[134:135]
	ds_read_b128 v[188:191], v144 offset:32768
	ds_read_b128 v[192:195], v144 offset:33792
	ds_read_b128 v[196:199], v144 offset:34816
	ds_read_b128 v[200:203], v144 offset:35840
	ds_read_b128 v[204:207], v144 offset:36864
	ds_read_b128 v[218:221], v144 offset:37888
	ds_read_b128 v[222:225], v144 offset:38912
	ds_read_b128 v[226:229], v144 offset:39936
	global_load_lds_dwordx4 v[230:231], off
	v_lshl_add_u64 v[230:231], s[62:63], 0, v[132:133]
	s_mov_b32 m0, s74
	s_nop 0
	global_load_lds_dwordx4 v[230:231], off
	s_waitcnt vmcnt(8) lgkmcnt(0)
	s_setprio 1
	s_barrier
	v_mfma_f32_16x16x32_bf16 v[124:127], v[156:159], v[188:191], v[124:127]
	v_mfma_f32_16x16x32_bf16 v[120:123], v[164:167], v[188:191], v[120:123]
	v_mfma_f32_16x16x32_bf16 v[112:115], v[156:159], v[196:199], v[112:115]
	v_mfma_f32_16x16x32_bf16 v[104:107], v[164:167], v[196:199], v[104:107]
	v_mfma_f32_16x16x32_bf16 v[96:99], v[156:159], v[204:207], v[96:99]
	v_mfma_f32_16x16x32_bf16 v[88:91], v[164:167], v[204:207], v[88:91]
	v_mfma_f32_16x16x32_bf16 v[80:83], v[156:159], v[222:225], v[80:83]
	v_mfma_f32_16x16x32_bf16 v[72:75], v[164:167], v[222:225], v[72:75]
	v_mfma_f32_16x16x32_bf16 v[124:127], v[160:163], v[192:195], v[124:127]
	v_mfma_f32_16x16x32_bf16 v[120:123], v[168:171], v[192:195], v[120:123]
	v_mfma_f32_16x16x32_bf16 v[112:115], v[160:163], v[200:203], v[112:115]
	v_mfma_f32_16x16x32_bf16 v[104:107], v[168:171], v[200:203], v[104:107]
	v_mfma_f32_16x16x32_bf16 v[96:99], v[160:163], v[218:221], v[96:99]
	v_mfma_f32_16x16x32_bf16 v[88:91], v[168:171], v[218:221], v[88:91]
	v_mfma_f32_16x16x32_bf16 v[80:83], v[160:163], v[226:229], v[80:83]
	v_mfma_f32_16x16x32_bf16 v[72:75], v[168:171], v[226:229], v[72:75]
	s_setprio 0
	s_setprio 1
	v_mfma_f32_16x16x32_bf16 v[116:119], v[172:175], v[188:191], v[116:119]
	v_mfma_f32_16x16x32_bf16 v[108:111], v[180:183], v[188:191], v[108:111]
	v_mfma_f32_16x16x32_bf16 v[100:103], v[172:175], v[196:199], v[100:103]
	v_mfma_f32_16x16x32_bf16 v[92:95], v[180:183], v[196:199], v[92:95]
	v_mfma_f32_16x16x32_bf16 v[84:87], v[172:175], v[204:207], v[84:87]
	v_mfma_f32_16x16x32_bf16 v[76:79], v[180:183], v[204:207], v[76:79]
	v_mfma_f32_16x16x32_bf16 v[68:71], v[172:175], v[222:225], v[68:71]
	v_mfma_f32_16x16x32_bf16 v[64:67], v[180:183], v[222:225], v[64:67]
	v_mfma_f32_16x16x32_bf16 v[116:119], v[176:179], v[192:195], v[116:119]
	v_mfma_f32_16x16x32_bf16 v[108:111], v[184:187], v[192:195], v[108:111]
	v_mfma_f32_16x16x32_bf16 v[100:103], v[176:179], v[200:203], v[100:103]
	v_mfma_f32_16x16x32_bf16 v[92:95], v[184:187], v[200:203], v[92:95]
	v_mfma_f32_16x16x32_bf16 v[84:87], v[176:179], v[218:221], v[84:87]
	v_mfma_f32_16x16x32_bf16 v[76:79], v[184:187], v[218:221], v[76:79]
	v_mfma_f32_16x16x32_bf16 v[68:71], v[176:179], v[226:229], v[68:71]
	v_mfma_f32_16x16x32_bf16 v[64:67], v[184:187], v[226:229], v[64:67]
	s_barrier
	s_setprio 0
	s_add_i32 s62, s85, s70
	v_lshl_add_u64 v[140:141], v[140:141], 0, s[0:1]
	s_mov_b32 m0, s62
	ds_read_b128 v[188:191], v144 offset:49152
	ds_read_b128 v[192:195], v144 offset:50176
	ds_read_b128 v[196:199], v144 offset:51200
	ds_read_b128 v[200:203], v144 offset:52224
	ds_read_b128 v[204:207], v144 offset:53248
	ds_read_b128 v[218:221], v144 offset:54272
	ds_read_b128 v[222:225], v144 offset:55296
	ds_read_b128 v[226:229], v144 offset:56320
	global_load_lds_dwordx4 v[140:141], off
	s_add_i32 m0, s62, 0x2000
	s_add_u32 s60, s60, 0x40080
	v_lshl_add_u64 v[140:141], v[146:147], 0, s[0:1]
	s_addc_u32 s61, s61, 0
	s_add_i32 s62, s88, s70
	global_load_lds_dwordx4 v[140:141], off
	v_lshl_add_u64 v[140:141], s[60:61], 0, v[148:149]
	s_mov_b32 m0, s62
	s_nop 0
	global_load_lds_dwordx4 v[140:141], off
	v_lshl_add_u64 v[140:141], s[60:61], 0, v[130:131]
	s_add_i32 m0, s62, 0x2000
	s_nop 0
	global_load_lds_dwordx4 v[140:141], off
	v_lshl_add_u64 v[140:141], v[208:209], 0, s[0:1]
	s_mov_b32 m0, s75
	s_nop 0
	global_load_lds_dwordx4 v[140:141], off
	v_lshl_add_u64 v[140:141], v[212:213], 0, s[0:1]
	s_mov_b32 m0, s76
	s_nop 0
	global_load_lds_dwordx4 v[140:141], off
	s_waitcnt vmcnt(8) lgkmcnt(0)
	s_setprio 1
	s_barrier
	v_mfma_f32_16x16x32_bf16 v[60:63], v[156:159], v[188:191], v[60:63]
	v_mfma_f32_16x16x32_bf16 v[56:59], v[164:167], v[188:191], v[56:59]
	v_mfma_f32_16x16x32_bf16 v[48:51], v[156:159], v[196:199], v[48:51]
	v_mfma_f32_16x16x32_bf16 v[40:43], v[164:167], v[196:199], v[40:43]
	v_mfma_f32_16x16x32_bf16 v[32:35], v[156:159], v[204:207], v[32:35]
	v_mfma_f32_16x16x32_bf16 v[24:27], v[164:167], v[204:207], v[24:27]
	v_mfma_f32_16x16x32_bf16 v[16:19], v[156:159], v[222:225], v[16:19]
	v_mfma_f32_16x16x32_bf16 v[8:11], v[164:167], v[222:225], v[8:11]
	v_mfma_f32_16x16x32_bf16 v[60:63], v[160:163], v[192:195], v[60:63]
	v_mfma_f32_16x16x32_bf16 v[56:59], v[168:171], v[192:195], v[56:59]
	v_mfma_f32_16x16x32_bf16 v[48:51], v[160:163], v[200:203], v[48:51]
	v_mfma_f32_16x16x32_bf16 v[40:43], v[168:171], v[200:203], v[40:43]
	v_mfma_f32_16x16x32_bf16 v[32:35], v[160:163], v[218:221], v[32:35]
	v_mfma_f32_16x16x32_bf16 v[24:27], v[168:171], v[218:221], v[24:27]
	v_mfma_f32_16x16x32_bf16 v[16:19], v[160:163], v[226:229], v[16:19]
	v_mfma_f32_16x16x32_bf16 v[8:11], v[168:171], v[226:229], v[8:11]
	s_setprio 0
	s_setprio 1
	v_mfma_f32_16x16x32_bf16 v[52:55], v[172:175], v[188:191], v[52:55]
	v_mfma_f32_16x16x32_bf16 v[44:47], v[180:183], v[188:191], v[44:47]
	v_mfma_f32_16x16x32_bf16 v[36:39], v[172:175], v[196:199], v[36:39]
	v_mfma_f32_16x16x32_bf16 v[28:31], v[180:183], v[196:199], v[28:31]
	v_mfma_f32_16x16x32_bf16 v[20:23], v[172:175], v[204:207], v[20:23]
	v_mfma_f32_16x16x32_bf16 v[12:15], v[180:183], v[204:207], v[12:15]
	v_mfma_f32_16x16x32_bf16 v[4:7], v[172:175], v[222:225], v[4:7]
	v_mfma_f32_16x16x32_bf16 v[0:3], v[180:183], v[222:225], v[0:3]
	v_mfma_f32_16x16x32_bf16 v[52:55], v[176:179], v[192:195], v[52:55]
	v_mfma_f32_16x16x32_bf16 v[44:47], v[184:187], v[192:195], v[44:47]
	v_mfma_f32_16x16x32_bf16 v[36:39], v[176:179], v[200:203], v[36:39]
	v_mfma_f32_16x16x32_bf16 v[28:31], v[184:187], v[200:203], v[28:31]
	v_mfma_f32_16x16x32_bf16 v[20:23], v[176:179], v[218:221], v[20:23]
	v_mfma_f32_16x16x32_bf16 v[12:15], v[184:187], v[218:221], v[12:15]
	v_mfma_f32_16x16x32_bf16 v[4:7], v[176:179], v[226:229], v[4:7]
	v_mfma_f32_16x16x32_bf16 v[0:3], v[184:187], v[226:229], v[0:3]
	s_barrier
	s_setprio 0
	s_add_i32 s84, s84, 2
	s_add_u32 s82, s82, 0x100
	s_addc_u32 s83, s83, 0
	s_add_u32 s58, s58, 0x100
	s_addc_u32 s59, s59, 0
	s_cmp_gt_u32 s84, 13
	s_cbranch_scc0 .LBB0_289
	s_andn2_b64 vcc, s[38:39], s[40:41]
	s_cbranch_vccz .LBB0_292
	s_barrier

.LBB0_738:
	s_add_u32 s38, s24, s36
	s_addc_u32 s39, s25, s37
	s_add_u32 s38, s38, 0x100
	s_addc_u32 s39, s39, 0
	s_add_u32 s71, s64, s36
	s_addc_u32 s72, s65, s37
	s_add_i32 s73, 0, 0x10000
	s_cmpk_eq_i32 s36, 0x700
	s_cselect_b32 s45, s29, s39
	s_cselect_b32 s44, s68, s38
	v_add_u32_e32 v143, s73, v141
	s_cselect_b32 s39, s27, s72
	s_cselect_b32 s38, s69, s71
	s_add_i32 s71, 0, 0x14000
	ds_read_b128 v[144:147], v143
	ds_read_b128 v[156:159], v143 offset:1024
	ds_read_b128 v[160:163], v143 offset:2048
	ds_read_b128 v[164:167], v143 offset:3072
	v_add_u32_e32 v143, s71, v141
	ds_read_b128 v[168:171], v143
	ds_read_b128 v[172:175], v143 offset:1024
	ds_read_b128 v[176:179], v143 offset:2048
	ds_read_b128 v[180:183], v143 offset:3072
	v_lshl_add_u64 v[154:155], v[138:139], 0, s[36:37]
	s_add_i32 m0, s48, 0xc000
	ds_read_b128 v[184:187], v142
	ds_read_b128 v[188:191], v142 offset:1024
	ds_read_b128 v[192:195], v142 offset:2048
	ds_read_b128 v[196:199], v142 offset:3072
	ds_read_b128 v[200:203], v142 offset:4096
	ds_read_b128 v[204:207], v142 offset:5120
	ds_read_b128 v[218:221], v142 offset:6144
	ds_read_b128 v[222:225], v142 offset:7168
	global_load_lds_dwordx4 v[154:155], off
	v_lshl_add_u64 v[154:155], v[136:137], 0, s[36:37]
	s_add_i32 m0, s48, 0xe000
	s_nop 0
	global_load_lds_dwordx4 v[154:155], off
	s_waitcnt vmcnt(8) lgkmcnt(0)
	s_setprio 1
	s_barrier
	v_mfma_f32_16x16x32_bf16 v[124:127], v[144:147], v[184:187], v[124:127]
	v_mfma_f32_16x16x32_bf16 v[120:123], v[160:163], v[184:187], v[120:123]
	v_mfma_f32_16x16x32_bf16 v[108:111], v[144:147], v[192:195], v[108:111]
	v_mfma_f32_16x16x32_bf16 v[104:107], v[160:163], v[192:195], v[104:107]
	v_mfma_f32_16x16x32_bf16 v[92:95], v[144:147], v[200:203], v[92:95]
	v_mfma_f32_16x16x32_bf16 v[88:91], v[160:163], v[200:203], v[88:91]
	v_mfma_f32_16x16x32_bf16 v[76:79], v[144:147], v[218:221], v[76:79]
	v_mfma_f32_16x16x32_bf16 v[72:75], v[160:163], v[218:221], v[72:75]
	v_mfma_f32_16x16x32_bf16 v[124:127], v[156:159], v[188:191], v[124:127]
	v_mfma_f32_16x16x32_bf16 v[120:123], v[164:167], v[188:191], v[120:123]
	v_mfma_f32_16x16x32_bf16 v[108:111], v[156:159], v[196:199], v[108:111]
	v_mfma_f32_16x16x32_bf16 v[104:107], v[164:167], v[196:199], v[104:107]
	v_mfma_f32_16x16x32_bf16 v[92:95], v[156:159], v[204:207], v[92:95]
	v_mfma_f32_16x16x32_bf16 v[88:91], v[164:167], v[204:207], v[88:91]
	v_mfma_f32_16x16x32_bf16 v[76:79], v[156:159], v[222:225], v[76:79]
	v_mfma_f32_16x16x32_bf16 v[72:75], v[164:167], v[222:225], v[72:75]
	s_setprio 0
	s_setprio 1
	v_mfma_f32_16x16x32_bf16 v[116:119], v[168:171], v[184:187], v[116:119]
	v_mfma_f32_16x16x32_bf16 v[112:115], v[176:179], v[184:187], v[112:115]
	v_mfma_f32_16x16x32_bf16 v[100:103], v[168:171], v[192:195], v[100:103]
	v_mfma_f32_16x16x32_bf16 v[96:99], v[176:179], v[192:195], v[96:99]
	v_mfma_f32_16x16x32_bf16 v[84:87], v[168:171], v[200:203], v[84:87]
	v_mfma_f32_16x16x32_bf16 v[80:83], v[176:179], v[200:203], v[80:83]
	v_mfma_f32_16x16x32_bf16 v[68:71], v[168:171], v[218:221], v[68:71]
	v_mfma_f32_16x16x32_bf16 v[64:67], v[176:179], v[218:221], v[64:67]
	v_mfma_f32_16x16x32_bf16 v[116:119], v[172:175], v[188:191], v[116:119]
	v_mfma_f32_16x16x32_bf16 v[112:115], v[180:183], v[188:191], v[112:115]
	v_mfma_f32_16x16x32_bf16 v[100:103], v[172:175], v[196:199], v[100:103]
	v_mfma_f32_16x16x32_bf16 v[96:99], v[180:183], v[196:199], v[96:99]
	v_mfma_f32_16x16x32_bf16 v[84:87], v[172:175], v[204:207], v[84:87]
	v_mfma_f32_16x16x32_bf16 v[80:83], v[180:183], v[204:207], v[80:83]
	v_mfma_f32_16x16x32_bf16 v[68:71], v[172:175], v[222:225], v[68:71]
	v_mfma_f32_16x16x32_bf16 v[64:67], v[180:183], v[222:225], v[64:67]
	s_barrier
	s_setprio 0
	s_add_i32 s72, s73, s47
	v_lshl_add_u64 v[154:155], s[38:39], 0, v[148:149]
	s_mov_b32 m0, s72
	ds_read_b128 v[184:187], v142 offset:16384
	ds_read_b128 v[188:191], v142 offset:17408
	ds_read_b128 v[192:195], v142 offset:18432
	ds_read_b128 v[196:199], v142 offset:19456
	ds_read_b128 v[200:203], v142 offset:20480
	ds_read_b128 v[204:207], v142 offset:21504
	ds_read_b128 v[218:221], v142 offset:22528
	ds_read_b128 v[222:225], v142 offset:23552
	global_load_lds_dwordx4 v[154:155], off
	s_add_i32 m0, s72, 0x2000
	s_add_u32 s72, s38, 0x40000
	v_lshl_add_u64 v[208:209], s[38:39], 0, v[130:131]
	s_addc_u32 s73, s39, 0
	s_add_i32 s71, s71, s47
	global_load_lds_dwordx4 v[208:209], off
	v_lshl_add_u64 v[212:213], s[72:73], 0, v[148:149]
	s_mov_b32 m0, s71
	v_lshl_add_u64 v[226:227], s[44:45], 0, v[130:131]
	global_load_lds_dwordx4 v[212:213], off
	v_lshl_add_u64 v[212:213], s[72:73], 0, v[130:131]
	s_add_i32 m0, s71, 0x2000
	s_nop 0
	global_load_lds_dwordx4 v[212:213], off
	v_lshl_add_u64 v[212:213], s[44:45], 0, v[148:149]
	s_mov_b32 m0, s48
	s_nop 0
	global_load_lds_dwordx4 v[212:213], off
	s_mov_b32 m0, s49
	s_nop 0
	global_load_lds_dwordx4 v[226:227], off
	s_waitcnt vmcnt(8) lgkmcnt(0)
	s_setprio 1
	s_barrier
	v_mfma_f32_16x16x32_bf16 v[60:63], v[144:147], v[184:187], v[60:63]
	v_mfma_f32_16x16x32_bf16 v[56:59], v[160:163], v[184:187], v[56:59]
	v_mfma_f32_16x16x32_bf16 v[44:47], v[144:147], v[192:195], v[44:47]
	v_mfma_f32_16x16x32_bf16 v[40:43], v[160:163], v[192:195], v[40:43]
	v_mfma_f32_16x16x32_bf16 v[28:31], v[144:147], v[200:203], v[28:31]
	v_mfma_f32_16x16x32_bf16 v[24:27], v[160:163], v[200:203], v[24:27]
	v_mfma_f32_16x16x32_bf16 v[12:15], v[144:147], v[218:221], v[12:15]
	v_mfma_f32_16x16x32_bf16 v[8:11], v[160:163], v[218:221], v[8:11]
	v_mfma_f32_16x16x32_bf16 v[60:63], v[156:159], v[188:191], v[60:63]
	v_mfma_f32_16x16x32_bf16 v[56:59], v[164:167], v[188:191], v[56:59]
	v_mfma_f32_16x16x32_bf16 v[44:47], v[156:159], v[196:199], v[44:47]
	v_mfma_f32_16x16x32_bf16 v[40:43], v[164:167], v[196:199], v[40:43]
	v_mfma_f32_16x16x32_bf16 v[28:31], v[156:159], v[204:207], v[28:31]
	v_mfma_f32_16x16x32_bf16 v[24:27], v[164:167], v[204:207], v[24:27]
	v_mfma_f32_16x16x32_bf16 v[12:15], v[156:159], v[222:225], v[12:15]
	v_mfma_f32_16x16x32_bf16 v[8:11], v[164:167], v[222:225], v[8:11]
	s_setprio 0
	s_setprio 1
	v_mfma_f32_16x16x32_bf16 v[52:55], v[168:171], v[184:187], v[52:55]
	v_mfma_f32_16x16x32_bf16 v[48:51], v[176:179], v[184:187], v[48:51]
	v_mfma_f32_16x16x32_bf16 v[36:39], v[168:171], v[192:195], v[36:39]
	v_mfma_f32_16x16x32_bf16 v[32:35], v[176:179], v[192:195], v[32:35]
	v_mfma_f32_16x16x32_bf16 v[20:23], v[168:171], v[200:203], v[20:23]
	v_mfma_f32_16x16x32_bf16 v[16:19], v[176:179], v[200:203], v[16:19]
	v_mfma_f32_16x16x32_bf16 v[4:7], v[168:171], v[218:221], v[4:7]
	v_mfma_f32_16x16x32_bf16 v[0:3], v[176:179], v[218:221], v[0:3]
	v_mfma_f32_16x16x32_bf16 v[52:55], v[172:175], v[188:191], v[52:55]
	v_mfma_f32_16x16x32_bf16 v[48:51], v[180:183], v[188:191], v[48:51]
	v_mfma_f32_16x16x32_bf16 v[36:39], v[172:175], v[196:199], v[36:39]
	v_mfma_f32_16x16x32_bf16 v[32:35], v[180:183], v[196:199], v[32:35]
	v_mfma_f32_16x16x32_bf16 v[20:23], v[172:175], v[204:207], v[20:23]
	v_mfma_f32_16x16x32_bf16 v[16:19], v[180:183], v[204:207], v[16:19]
	v_mfma_f32_16x16x32_bf16 v[4:7], v[172:175], v[222:225], v[4:7]
	v_mfma_f32_16x16x32_bf16 v[0:3], v[180:183], v[222:225], v[0:3]
	s_barrier
	s_setprio 0
	s_add_i32 s71, 0, 0x18000
	v_add_u32_e32 v143, s71, v141
	s_add_i32 s72, 0, 0x1c000
	ds_read_b128 v[144:147], v143
	ds_read_b128 v[156:159], v143 offset:1024
	ds_read_b128 v[160:163], v143 offset:2048
	ds_read_b128 v[164:167], v143 offset:3072
	v_add_u32_e32 v143, s72, v141
	ds_read_b128 v[168:171], v143
	ds_read_b128 v[172:175], v143 offset:1024
	ds_read_b128 v[176:179], v143 offset:2048
	ds_read_b128 v[180:183], v143 offset:3072
	s_add_u32 s44, s44, 0x40000
	s_addc_u32 s45, s45, 0
	s_mov_b32 m0, s58
	v_lshl_add_u64 v[228:229], s[44:45], 0, v[148:149]
	ds_read_b128 v[184:187], v142 offset:32768
	ds_read_b128 v[188:191], v142 offset:33792
	ds_read_b128 v[192:195], v142 offset:34816
	ds_read_b128 v[196:199], v142 offset:35840
	ds_read_b128 v[200:203], v142 offset:36864
	ds_read_b128 v[204:207], v142 offset:37888
	ds_read_b128 v[218:221], v142 offset:38912
	ds_read_b128 v[222:225], v142 offset:39936
	global_load_lds_dwordx4 v[228:229], off
	v_lshl_add_u64 v[228:229], s[44:45], 0, v[130:131]
	s_mov_b32 m0, s59
	s_nop 0
	global_load_lds_dwordx4 v[228:229], off
	s_waitcnt vmcnt(8) lgkmcnt(0)
	s_setprio 1
	s_barrier
	v_mfma_f32_16x16x32_bf16 v[124:127], v[144:147], v[184:187], v[124:127]
	v_mfma_f32_16x16x32_bf16 v[120:123], v[160:163], v[184:187], v[120:123]
	v_mfma_f32_16x16x32_bf16 v[108:111], v[144:147], v[192:195], v[108:111]
	v_mfma_f32_16x16x32_bf16 v[104:107], v[160:163], v[192:195], v[104:107]
	v_mfma_f32_16x16x32_bf16 v[92:95], v[144:147], v[200:203], v[92:95]
	v_mfma_f32_16x16x32_bf16 v[88:91], v[160:163], v[200:203], v[88:91]
	v_mfma_f32_16x16x32_bf16 v[76:79], v[144:147], v[218:221], v[76:79]
	v_mfma_f32_16x16x32_bf16 v[72:75], v[160:163], v[218:221], v[72:75]
	v_mfma_f32_16x16x32_bf16 v[124:127], v[156:159], v[188:191], v[124:127]
	v_mfma_f32_16x16x32_bf16 v[120:123], v[164:167], v[188:191], v[120:123]
	v_mfma_f32_16x16x32_bf16 v[108:111], v[156:159], v[196:199], v[108:111]
	v_mfma_f32_16x16x32_bf16 v[104:107], v[164:167], v[196:199], v[104:107]
	v_mfma_f32_16x16x32_bf16 v[92:95], v[156:159], v[204:207], v[92:95]
	v_mfma_f32_16x16x32_bf16 v[88:91], v[164:167], v[204:207], v[88:91]
	v_mfma_f32_16x16x32_bf16 v[76:79], v[156:159], v[222:225], v[76:79]
	v_mfma_f32_16x16x32_bf16 v[72:75], v[164:167], v[222:225], v[72:75]
	s_setprio 0
	s_setprio 1
	v_mfma_f32_16x16x32_bf16 v[116:119], v[168:171], v[184:187], v[116:119]
	v_mfma_f32_16x16x32_bf16 v[112:115], v[176:179], v[184:187], v[112:115]
	v_mfma_f32_16x16x32_bf16 v[100:103], v[168:171], v[192:195], v[100:103]
	v_mfma_f32_16x16x32_bf16 v[96:99], v[176:179], v[192:195], v[96:99]
	v_mfma_f32_16x16x32_bf16 v[84:87], v[168:171], v[200:203], v[84:87]
	v_mfma_f32_16x16x32_bf16 v[80:83], v[176:179], v[200:203], v[80:83]
	v_mfma_f32_16x16x32_bf16 v[68:71], v[168:171], v[218:221], v[68:71]
	v_mfma_f32_16x16x32_bf16 v[64:67], v[176:179], v[218:221], v[64:67]
	v_mfma_f32_16x16x32_bf16 v[116:119], v[172:175], v[188:191], v[116:119]
	v_mfma_f32_16x16x32_bf16 v[112:115], v[180:183], v[188:191], v[112:115]
	v_mfma_f32_16x16x32_bf16 v[100:103], v[172:175], v[196:199], v[100:103]
	v_mfma_f32_16x16x32_bf16 v[96:99], v[180:183], v[196:199], v[96:99]
	v_mfma_f32_16x16x32_bf16 v[84:87], v[172:175], v[204:207], v[84:87]
	v_mfma_f32_16x16x32_bf16 v[80:83], v[180:183], v[204:207], v[80:83]
	v_mfma_f32_16x16x32_bf16 v[68:71], v[172:175], v[222:225], v[68:71]
	v_mfma_f32_16x16x32_bf16 v[64:67], v[180:183], v[222:225], v[64:67]
	s_barrier
	s_setprio 0
	s_add_i32 s44, s71, s47
	v_lshl_add_u64 v[154:155], v[154:155], 0, s[0:1]
	s_mov_b32 m0, s44
	ds_read_b128 v[184:187], v142 offset:49152
	ds_read_b128 v[188:191], v142 offset:50176
	ds_read_b128 v[192:195], v142 offset:51200
	ds_read_b128 v[196:199], v142 offset:52224
	ds_read_b128 v[200:203], v142 offset:53248
	ds_read_b128 v[204:207], v142 offset:54272
	ds_read_b128 v[218:221], v142 offset:55296
	ds_read_b128 v[222:225], v142 offset:56320
	global_load_lds_dwordx4 v[154:155], off
	s_add_i32 m0, s44, 0x2000
	s_add_u32 s38, s38, 0x40080
	v_lshl_add_u64 v[154:155], v[208:209], 0, s[0:1]
	s_addc_u32 s39, s39, 0
	s_add_i32 s44, s72, s47
	global_load_lds_dwordx4 v[154:155], off
	v_lshl_add_u64 v[154:155], s[38:39], 0, v[148:149]
	s_mov_b32 m0, s44
	s_nop 0
	global_load_lds_dwordx4 v[154:155], off
	v_lshl_add_u64 v[154:155], s[38:39], 0, v[130:131]
	s_add_i32 m0, s44, 0x2000
	s_nop 0
	global_load_lds_dwordx4 v[154:155], off
	v_lshl_add_u64 v[154:155], v[212:213], 0, s[0:1]
	s_mov_b32 m0, s60
	s_nop 0
	global_load_lds_dwordx4 v[154:155], off
	v_lshl_add_u64 v[154:155], v[226:227], 0, s[0:1]
	s_mov_b32 m0, s61
	s_nop 0
	global_load_lds_dwordx4 v[154:155], off
	s_waitcnt vmcnt(8) lgkmcnt(0)
	s_setprio 1
	s_barrier
	v_mfma_f32_16x16x32_bf16 v[60:63], v[144:147], v[184:187], v[60:63]
	v_mfma_f32_16x16x32_bf16 v[56:59], v[160:163], v[184:187], v[56:59]
	v_mfma_f32_16x16x32_bf16 v[44:47], v[144:147], v[192:195], v[44:47]
	v_mfma_f32_16x16x32_bf16 v[40:43], v[160:163], v[192:195], v[40:43]
	v_mfma_f32_16x16x32_bf16 v[28:31], v[144:147], v[200:203], v[28:31]
	v_mfma_f32_16x16x32_bf16 v[24:27], v[160:163], v[200:203], v[24:27]
	v_mfma_f32_16x16x32_bf16 v[12:15], v[144:147], v[218:221], v[12:15]
	v_mfma_f32_16x16x32_bf16 v[8:11], v[160:163], v[218:221], v[8:11]
	v_mfma_f32_16x16x32_bf16 v[60:63], v[156:159], v[188:191], v[60:63]
	v_mfma_f32_16x16x32_bf16 v[56:59], v[164:167], v[188:191], v[56:59]
	v_mfma_f32_16x16x32_bf16 v[44:47], v[156:159], v[196:199], v[44:47]
	v_mfma_f32_16x16x32_bf16 v[40:43], v[164:167], v[196:199], v[40:43]
	v_mfma_f32_16x16x32_bf16 v[28:31], v[156:159], v[204:207], v[28:31]
	v_mfma_f32_16x16x32_bf16 v[24:27], v[164:167], v[204:207], v[24:27]
	v_mfma_f32_16x16x32_bf16 v[12:15], v[156:159], v[222:225], v[12:15]
	v_mfma_f32_16x16x32_bf16 v[8:11], v[164:167], v[222:225], v[8:11]
	s_setprio 0
	s_setprio 1
	v_mfma_f32_16x16x32_bf16 v[52:55], v[168:171], v[184:187], v[52:55]
	v_mfma_f32_16x16x32_bf16 v[48:51], v[176:179], v[184:187], v[48:51]
	v_mfma_f32_16x16x32_bf16 v[36:39], v[168:171], v[192:195], v[36:39]
	v_mfma_f32_16x16x32_bf16 v[32:35], v[176:179], v[192:195], v[32:35]
	v_mfma_f32_16x16x32_bf16 v[20:23], v[168:171], v[200:203], v[20:23]
	v_mfma_f32_16x16x32_bf16 v[16:19], v[176:179], v[200:203], v[16:19]
	v_mfma_f32_16x16x32_bf16 v[4:7], v[168:171], v[218:221], v[4:7]
	v_mfma_f32_16x16x32_bf16 v[0:3], v[176:179], v[218:221], v[0:3]
	v_mfma_f32_16x16x32_bf16 v[52:55], v[172:175], v[188:191], v[52:55]
	v_mfma_f32_16x16x32_bf16 v[48:51], v[180:183], v[188:191], v[48:51]
	v_mfma_f32_16x16x32_bf16 v[36:39], v[172:175], v[196:199], v[36:39]
	v_mfma_f32_16x16x32_bf16 v[32:35], v[180:183], v[196:199], v[32:35]
	v_mfma_f32_16x16x32_bf16 v[20:23], v[172:175], v[204:207], v[20:23]
	v_mfma_f32_16x16x32_bf16 v[16:19], v[180:183], v[204:207], v[16:19]
	v_mfma_f32_16x16x32_bf16 v[4:7], v[172:175], v[222:225], v[4:7]
	v_mfma_f32_16x16x32_bf16 v[0:3], v[180:183], v[222:225], v[0:3]
	s_barrier
	s_setprio 0
	s_add_i32 s70, s70, 2
	s_add_u32 s36, s36, 0x100
	s_addc_u32 s37, s37, 0
	s_cmp_gt_u32 s70, 13
	s_cbranch_scc0 .LBB0_738
	s_add_u32 s36, s64, 0xffffff00
	s_addc_u32 s37, s65, -1
	s_andn2_b64 vcc, exec, s[42:43]
	s_cbranch_vccnz .LBB0_741
	v_mov_b32_e32 v0, 0
	s_mov_b32 s4, s26
	s_mov_b32 s22, s28
	s_mov_b64 s[24:25], s[34:35]
	s_mov_b32 s62, s63
	v_mov_b32_e32 v1, v0
	v_mov_b32_e32 v2, v0
	v_mov_b32_e32 v3, v0
	v_mov_b32_e32 v4, v0
	v_mov_b32_e32 v5, v0
	v_mov_b32_e32 v6, v0
	v_mov_b32_e32 v7, v0
	v_mov_b32_e32 v16, v0
	v_mov_b32_e32 v17, v0
	v_mov_b32_e32 v18, v0
	v_mov_b32_e32 v19, v0
	v_mov_b32_e32 v20, v0
	v_mov_b32_e32 v21, v0
	v_mov_b32_e32 v22, v0
	v_mov_b32_e32 v23, v0
	v_mov_b32_e32 v32, v0
	v_mov_b32_e32 v33, v0
	v_mov_b32_e32 v34, v0
	v_mov_b32_e32 v35, v0
	v_mov_b32_e32 v36, v0
	v_mov_b32_e32 v37, v0
	v_mov_b32_e32 v38, v0
	v_mov_b32_e32 v39, v0
	v_mov_b32_e32 v48, v0
	v_mov_b32_e32 v49, v0
	v_mov_b32_e32 v50, v0
	v_mov_b32_e32 v51, v0
	v_mov_b32_e32 v52, v0
	v_mov_b32_e32 v53, v0
	v_mov_b32_e32 v54, v0
	v_mov_b32_e32 v55, v0
	v_mov_b32_e32 v8, v0
	v_mov_b32_e32 v9, v0
	v_mov_b32_e32 v10, v0
	v_mov_b32_e32 v11, v0
	v_mov_b32_e32 v12, v0
	v_mov_b32_e32 v13, v0
	v_mov_b32_e32 v14, v0
	v_mov_b32_e32 v15, v0
	v_mov_b32_e32 v24, v0
	v_mov_b32_e32 v25, v0
	v_mov_b32_e32 v26, v0
	v_mov_b32_e32 v27, v0
	v_mov_b32_e32 v28, v0
	v_mov_b32_e32 v29, v0
	v_mov_b32_e32 v30, v0
	v_mov_b32_e32 v31, v0
	v_mov_b32_e32 v40, v0
	v_mov_b32_e32 v41, v0
	v_mov_b32_e32 v42, v0
	v_mov_b32_e32 v43, v0
	v_mov_b32_e32 v44, v0
	v_mov_b32_e32 v45, v0
	v_mov_b32_e32 v46, v0
	v_mov_b32_e32 v47, v0
	v_mov_b32_e32 v56, v0
	v_mov_b32_e32 v57, v0
	v_mov_b32_e32 v58, v0
	v_mov_b32_e32 v59, v0
	v_mov_b32_e32 v60, v0
	v_mov_b32_e32 v61, v0
	v_mov_b32_e32 v62, v0
	v_mov_b32_e32 v63, v0
	v_mov_b32_e32 v64, v0
	v_mov_b32_e32 v65, v0
	v_mov_b32_e32 v66, v0
	v_mov_b32_e32 v67, v0
	v_mov_b32_e32 v68, v0
	v_mov_b32_e32 v69, v0
	v_mov_b32_e32 v70, v0
	v_mov_b32_e32 v71, v0
	v_mov_b32_e32 v80, v0
	v_mov_b32_e32 v81, v0
	v_mov_b32_e32 v82, v0
	v_mov_b32_e32 v83, v0
	v_mov_b32_e32 v84, v0
	v_mov_b32_e32 v85, v0
	v_mov_b32_e32 v86, v0
	v_mov_b32_e32 v87, v0
	v_mov_b32_e32 v96, v0
	v_mov_b32_e32 v97, v0
	v_mov_b32_e32 v98, v0
	v_mov_b32_e32 v99, v0
	v_mov_b32_e32 v100, v0
	v_mov_b32_e32 v101, v0
	v_mov_b32_e32 v102, v0
	v_mov_b32_e32 v103, v0
	v_mov_b32_e32 v112, v0
	v_mov_b32_e32 v113, v0
	v_mov_b32_e32 v114, v0
	v_mov_b32_e32 v115, v0
	v_mov_b32_e32 v116, v0
	v_mov_b32_e32 v117, v0
	v_mov_b32_e32 v118, v0
	v_mov_b32_e32 v119, v0
	v_mov_b32_e32 v72, v0
	v_mov_b32_e32 v73, v0
	v_mov_b32_e32 v74, v0
	v_mov_b32_e32 v75, v0
	v_mov_b32_e32 v76, v0
	v_mov_b32_e32 v77, v0
	v_mov_b32_e32 v78, v0
	v_mov_b32_e32 v79, v0
	v_mov_b32_e32 v88, v0
	v_mov_b32_e32 v89, v0
	v_mov_b32_e32 v90, v0
	v_mov_b32_e32 v91, v0
	v_mov_b32_e32 v92, v0
	v_mov_b32_e32 v93, v0
	v_mov_b32_e32 v94, v0
	v_mov_b32_e32 v95, v0
	v_mov_b32_e32 v104, v0
	v_mov_b32_e32 v105, v0
	v_mov_b32_e32 v106, v0
	v_mov_b32_e32 v107, v0
	v_mov_b32_e32 v108, v0
	v_mov_b32_e32 v109, v0
	v_mov_b32_e32 v110, v0
	v_mov_b32_e32 v111, v0
	v_mov_b32_e32 v120, v0
	v_mov_b32_e32 v121, v0
	v_mov_b32_e32 v122, v0
	v_mov_b32_e32 v123, v0
	v_mov_b32_e32 v124, v0
	v_mov_b32_e32 v125, v0
	v_mov_b32_e32 v126, v0
	v_mov_b32_e32 v127, v0
	s_andn2_b64 vcc, exec, s[40:41]
	s_cbranch_vccnz .LBB0_742
	s_branch .LBB0_743

.LBB0_841:
	s_lshl_b32 s60, s78, 7
	s_add_u32 s61, s24, s60
	s_addc_u32 s62, s25, 0
	s_add_u32 s63, s61, 0x100
	s_addc_u32 s79, s62, 0
	s_and_b64 s[58:59], s[48:49], exec
	s_cselect_b32 s59, s31, s79
	s_cselect_b32 s58, s35, s63
	s_add_u32 s60, s26, s60
	s_addc_u32 s63, s27, 0
	s_add_u32 s60, s60, 0x100
	s_addc_u32 s63, s63, 0
	s_and_b64 s[48:49], s[48:49], exec
	s_cselect_b32 s49, s29, s63
	s_cselect_b32 s48, s77, s60
	s_add_i32 s63, 0, 0x10000
	v_add_u32_e32 v146, s63, v132
	s_add_i32 s79, 0, 0x14000
	ds_read_b128 v[134:137], v146
	ds_read_b128 v[138:141], v146 offset:1024
	ds_read_b128 v[142:145], v146 offset:2048
	ds_read_b128 v[156:159], v146 offset:3072
	v_add_u32_e32 v146, s79, v132
	ds_read_b128 v[164:167], v146
	ds_read_b128 v[168:171], v146 offset:1024
	ds_read_b128 v[172:175], v146 offset:2048
	ds_read_b128 v[176:179], v146 offset:3072
	s_add_u32 s60, s61, 0x40080
	s_addc_u32 s61, s62, 0
	v_lshl_add_u64 v[146:147], s[60:61], 0, v[148:149]
	s_add_i32 m0, s70, 0xc000
	ds_read_b128 v[180:183], v133
	ds_read_b128 v[184:187], v133 offset:1024
	ds_read_b128 v[188:191], v133 offset:2048
	ds_read_b128 v[192:195], v133 offset:3072
	ds_read_b128 v[196:199], v133 offset:4096
	ds_read_b128 v[200:203], v133 offset:5120
	ds_read_b128 v[204:207], v133 offset:6144
	ds_read_b128 v[218:221], v133 offset:7168
	global_load_lds_dwordx4 v[146:147], off
	v_lshl_add_u64 v[146:147], s[60:61], 0, v[130:131]
	s_add_i32 m0, s70, 0xe000
	s_nop 0
	global_load_lds_dwordx4 v[146:147], off
	s_waitcnt vmcnt(8) lgkmcnt(0)
	s_setprio 1
	s_barrier
	v_mfma_f32_16x16x32_bf16 v[124:127], v[134:137], v[180:183], v[124:127]
	v_mfma_f32_16x16x32_bf16 v[120:123], v[142:145], v[180:183], v[120:123]
	v_mfma_f32_16x16x32_bf16 v[112:115], v[134:137], v[188:191], v[112:115]
	v_mfma_f32_16x16x32_bf16 v[104:107], v[142:145], v[188:191], v[104:107]
	v_mfma_f32_16x16x32_bf16 v[92:95], v[134:137], v[196:199], v[92:95]
	v_mfma_f32_16x16x32_bf16 v[88:91], v[142:145], v[196:199], v[88:91]
	v_mfma_f32_16x16x32_bf16 v[76:79], v[134:137], v[204:207], v[76:79]
	v_mfma_f32_16x16x32_bf16 v[72:75], v[142:145], v[204:207], v[72:75]
	v_mfma_f32_16x16x32_bf16 v[124:127], v[138:141], v[184:187], v[124:127]
	v_mfma_f32_16x16x32_bf16 v[120:123], v[156:159], v[184:187], v[120:123]
	v_mfma_f32_16x16x32_bf16 v[112:115], v[138:141], v[192:195], v[112:115]
	v_mfma_f32_16x16x32_bf16 v[104:107], v[156:159], v[192:195], v[104:107]
	v_mfma_f32_16x16x32_bf16 v[92:95], v[138:141], v[200:203], v[92:95]
	v_mfma_f32_16x16x32_bf16 v[88:91], v[156:159], v[200:203], v[88:91]
	v_mfma_f32_16x16x32_bf16 v[76:79], v[138:141], v[218:221], v[76:79]
	v_mfma_f32_16x16x32_bf16 v[72:75], v[156:159], v[218:221], v[72:75]
	s_setprio 0
	s_setprio 1
	v_mfma_f32_16x16x32_bf16 v[116:119], v[164:167], v[180:183], v[116:119]
	v_mfma_f32_16x16x32_bf16 v[108:111], v[172:175], v[180:183], v[108:111]
	v_mfma_f32_16x16x32_bf16 v[100:103], v[164:167], v[188:191], v[100:103]
	v_mfma_f32_16x16x32_bf16 v[96:99], v[172:175], v[188:191], v[96:99]
	v_mfma_f32_16x16x32_bf16 v[84:87], v[164:167], v[196:199], v[84:87]
	v_mfma_f32_16x16x32_bf16 v[80:83], v[172:175], v[196:199], v[80:83]
	v_mfma_f32_16x16x32_bf16 v[68:71], v[164:167], v[204:207], v[68:71]
	v_mfma_f32_16x16x32_bf16 v[64:67], v[172:175], v[204:207], v[64:67]
	v_mfma_f32_16x16x32_bf16 v[116:119], v[168:171], v[184:187], v[116:119]
	v_mfma_f32_16x16x32_bf16 v[108:111], v[176:179], v[184:187], v[108:111]
	v_mfma_f32_16x16x32_bf16 v[100:103], v[168:171], v[192:195], v[100:103]
	v_mfma_f32_16x16x32_bf16 v[96:99], v[176:179], v[192:195], v[96:99]
	v_mfma_f32_16x16x32_bf16 v[84:87], v[168:171], v[200:203], v[84:87]
	v_mfma_f32_16x16x32_bf16 v[80:83], v[176:179], v[200:203], v[80:83]
	v_mfma_f32_16x16x32_bf16 v[68:71], v[168:171], v[218:221], v[68:71]
	v_mfma_f32_16x16x32_bf16 v[64:67], v[176:179], v[218:221], v[64:67]
	s_barrier
	s_setprio 0
	s_add_i32 s60, s63, s69
	v_lshl_add_u64 v[146:147], s[48:49], 0, v[148:149]
	s_mov_b32 m0, s60
	ds_read_b128 v[180:183], v133 offset:16384
	ds_read_b128 v[184:187], v133 offset:17408
	ds_read_b128 v[188:191], v133 offset:18432
	ds_read_b128 v[192:195], v133 offset:19456
	ds_read_b128 v[196:199], v133 offset:20480
	ds_read_b128 v[200:203], v133 offset:21504
	ds_read_b128 v[204:207], v133 offset:22528
	ds_read_b128 v[218:221], v133 offset:23552
	global_load_lds_dwordx4 v[146:147], off
	s_add_i32 m0, s60, 0x2000
	s_add_u32 s60, s48, 0x40000
	v_lshl_add_u64 v[154:155], s[48:49], 0, v[130:131]
	s_addc_u32 s61, s49, 0
	s_add_i32 s62, s79, s69
	global_load_lds_dwordx4 v[154:155], off
	v_lshl_add_u64 v[160:161], s[60:61], 0, v[148:149]
	s_mov_b32 m0, s62
	v_lshl_add_u64 v[208:209], s[58:59], 0, v[130:131]
	global_load_lds_dwordx4 v[160:161], off
	v_lshl_add_u64 v[160:161], s[60:61], 0, v[130:131]
	s_add_i32 m0, s62, 0x2000
	s_nop 0
	global_load_lds_dwordx4 v[160:161], off
	v_lshl_add_u64 v[160:161], s[58:59], 0, v[148:149]
	s_mov_b32 m0, s70
	s_nop 0
	global_load_lds_dwordx4 v[160:161], off
	s_mov_b32 m0, s71
	s_nop 0
	global_load_lds_dwordx4 v[208:209], off
	s_waitcnt vmcnt(8) lgkmcnt(0)
	s_setprio 1
	s_barrier
	v_mfma_f32_16x16x32_bf16 v[60:63], v[134:137], v[180:183], v[60:63]
	v_mfma_f32_16x16x32_bf16 v[56:59], v[142:145], v[180:183], v[56:59]
	v_mfma_f32_16x16x32_bf16 v[44:47], v[134:137], v[188:191], v[44:47]
	v_mfma_f32_16x16x32_bf16 v[40:43], v[142:145], v[188:191], v[40:43]
	v_mfma_f32_16x16x32_bf16 v[28:31], v[134:137], v[196:199], v[28:31]
	v_mfma_f32_16x16x32_bf16 v[24:27], v[142:145], v[196:199], v[24:27]
	v_mfma_f32_16x16x32_bf16 v[12:15], v[134:137], v[204:207], v[12:15]
	v_mfma_f32_16x16x32_bf16 v[8:11], v[142:145], v[204:207], v[8:11]
	v_mfma_f32_16x16x32_bf16 v[60:63], v[138:141], v[184:187], v[60:63]
	v_mfma_f32_16x16x32_bf16 v[56:59], v[156:159], v[184:187], v[56:59]
	v_mfma_f32_16x16x32_bf16 v[44:47], v[138:141], v[192:195], v[44:47]
	v_mfma_f32_16x16x32_bf16 v[40:43], v[156:159], v[192:195], v[40:43]
	v_mfma_f32_16x16x32_bf16 v[28:31], v[138:141], v[200:203], v[28:31]
	v_mfma_f32_16x16x32_bf16 v[24:27], v[156:159], v[200:203], v[24:27]
	v_mfma_f32_16x16x32_bf16 v[12:15], v[138:141], v[218:221], v[12:15]
	v_mfma_f32_16x16x32_bf16 v[8:11], v[156:159], v[218:221], v[8:11]
	s_setprio 0
	s_setprio 1
	v_mfma_f32_16x16x32_bf16 v[52:55], v[164:167], v[180:183], v[52:55]
	v_mfma_f32_16x16x32_bf16 v[48:51], v[172:175], v[180:183], v[48:51]
	v_mfma_f32_16x16x32_bf16 v[36:39], v[164:167], v[188:191], v[36:39]
	v_mfma_f32_16x16x32_bf16 v[32:35], v[172:175], v[188:191], v[32:35]
	v_mfma_f32_16x16x32_bf16 v[20:23], v[164:167], v[196:199], v[20:23]
	v_mfma_f32_16x16x32_bf16 v[16:19], v[172:175], v[196:199], v[16:19]
	v_mfma_f32_16x16x32_bf16 v[4:7], v[164:167], v[204:207], v[4:7]
	v_mfma_f32_16x16x32_bf16 v[0:3], v[172:175], v[204:207], v[0:3]
	v_mfma_f32_16x16x32_bf16 v[52:55], v[168:171], v[184:187], v[52:55]
	v_mfma_f32_16x16x32_bf16 v[48:51], v[176:179], v[184:187], v[48:51]
	v_mfma_f32_16x16x32_bf16 v[36:39], v[168:171], v[192:195], v[36:39]
	v_mfma_f32_16x16x32_bf16 v[32:35], v[176:179], v[192:195], v[32:35]
	v_mfma_f32_16x16x32_bf16 v[20:23], v[168:171], v[200:203], v[20:23]
	v_mfma_f32_16x16x32_bf16 v[16:19], v[176:179], v[200:203], v[16:19]
	v_mfma_f32_16x16x32_bf16 v[4:7], v[168:171], v[218:221], v[4:7]
	v_mfma_f32_16x16x32_bf16 v[0:3], v[176:179], v[218:221], v[0:3]
	s_barrier
	s_setprio 0
	s_add_i32 s60, 0, 0x18000
	s_add_i32 s61, 0, 0x1c000
	v_add_u32_e32 v156, s60, v132
	v_add_u32_e32 v162, s61, v132
	ds_read_b128 v[134:137], v156
	ds_read_b128 v[138:141], v156 offset:1024
	ds_read_b128 v[142:145], v156 offset:2048
	ds_read_b128 v[156:159], v156 offset:3072
	ds_read_b128 v[164:167], v162
	ds_read_b128 v[168:171], v162 offset:1024
	ds_read_b128 v[172:175], v162 offset:2048
	ds_read_b128 v[176:179], v162 offset:3072
	s_add_u32 s58, s58, 0x40000
	s_addc_u32 s59, s59, 0
	s_mov_b32 m0, s72
	v_lshl_add_u64 v[212:213], s[58:59], 0, v[148:149]
	ds_read_b128 v[180:183], v133 offset:32768
	ds_read_b128 v[184:187], v133 offset:33792
	ds_read_b128 v[188:191], v133 offset:34816
	ds_read_b128 v[192:195], v133 offset:35840
	ds_read_b128 v[196:199], v133 offset:36864
	ds_read_b128 v[200:203], v133 offset:37888
	ds_read_b128 v[204:207], v133 offset:38912
	ds_read_b128 v[218:221], v133 offset:39936
	global_load_lds_dwordx4 v[212:213], off
	v_lshl_add_u64 v[212:213], s[58:59], 0, v[130:131]
	s_mov_b32 m0, s73
	s_nop 0
	global_load_lds_dwordx4 v[212:213], off
	s_waitcnt vmcnt(8) lgkmcnt(0)
	s_setprio 1
	s_barrier
	v_mfma_f32_16x16x32_bf16 v[124:127], v[134:137], v[180:183], v[124:127]
	v_mfma_f32_16x16x32_bf16 v[120:123], v[142:145], v[180:183], v[120:123]
	v_mfma_f32_16x16x32_bf16 v[112:115], v[134:137], v[188:191], v[112:115]
	v_mfma_f32_16x16x32_bf16 v[104:107], v[142:145], v[188:191], v[104:107]
	v_mfma_f32_16x16x32_bf16 v[92:95], v[134:137], v[196:199], v[92:95]
	v_mfma_f32_16x16x32_bf16 v[88:91], v[142:145], v[196:199], v[88:91]
	v_mfma_f32_16x16x32_bf16 v[76:79], v[134:137], v[204:207], v[76:79]
	v_mfma_f32_16x16x32_bf16 v[72:75], v[142:145], v[204:207], v[72:75]
	v_mfma_f32_16x16x32_bf16 v[124:127], v[138:141], v[184:187], v[124:127]
	v_mfma_f32_16x16x32_bf16 v[120:123], v[156:159], v[184:187], v[120:123]
	v_mfma_f32_16x16x32_bf16 v[112:115], v[138:141], v[192:195], v[112:115]
	v_mfma_f32_16x16x32_bf16 v[104:107], v[156:159], v[192:195], v[104:107]
	v_mfma_f32_16x16x32_bf16 v[92:95], v[138:141], v[200:203], v[92:95]
	v_mfma_f32_16x16x32_bf16 v[88:91], v[156:159], v[200:203], v[88:91]
	v_mfma_f32_16x16x32_bf16 v[76:79], v[138:141], v[218:221], v[76:79]
	v_mfma_f32_16x16x32_bf16 v[72:75], v[156:159], v[218:221], v[72:75]
	s_setprio 0
	s_setprio 1
	v_mfma_f32_16x16x32_bf16 v[116:119], v[164:167], v[180:183], v[116:119]
	v_mfma_f32_16x16x32_bf16 v[108:111], v[172:175], v[180:183], v[108:111]
	v_mfma_f32_16x16x32_bf16 v[100:103], v[164:167], v[188:191], v[100:103]
	v_mfma_f32_16x16x32_bf16 v[96:99], v[172:175], v[188:191], v[96:99]
	v_mfma_f32_16x16x32_bf16 v[84:87], v[164:167], v[196:199], v[84:87]
	v_mfma_f32_16x16x32_bf16 v[80:83], v[172:175], v[196:199], v[80:83]
	v_mfma_f32_16x16x32_bf16 v[68:71], v[164:167], v[204:207], v[68:71]
	v_mfma_f32_16x16x32_bf16 v[64:67], v[172:175], v[204:207], v[64:67]
	v_mfma_f32_16x16x32_bf16 v[116:119], v[168:171], v[184:187], v[116:119]
	v_mfma_f32_16x16x32_bf16 v[108:111], v[176:179], v[184:187], v[108:111]
	v_mfma_f32_16x16x32_bf16 v[100:103], v[168:171], v[192:195], v[100:103]
	v_mfma_f32_16x16x32_bf16 v[96:99], v[176:179], v[192:195], v[96:99]
	v_mfma_f32_16x16x32_bf16 v[84:87], v[168:171], v[200:203], v[84:87]
	v_mfma_f32_16x16x32_bf16 v[80:83], v[176:179], v[200:203], v[80:83]
	v_mfma_f32_16x16x32_bf16 v[68:71], v[168:171], v[218:221], v[68:71]
	v_mfma_f32_16x16x32_bf16 v[64:67], v[176:179], v[218:221], v[64:67]
	s_barrier
	s_setprio 0
	s_add_i32 s58, s60, s69
	v_lshl_add_u64 v[146:147], v[146:147], 0, s[0:1]
	s_mov_b32 m0, s58
	ds_read_b128 v[180:183], v133 offset:49152
	ds_read_b128 v[184:187], v133 offset:50176
	ds_read_b128 v[188:191], v133 offset:51200
	ds_read_b128 v[192:195], v133 offset:52224
	ds_read_b128 v[196:199], v133 offset:53248
	ds_read_b128 v[200:203], v133 offset:54272
	ds_read_b128 v[204:207], v133 offset:55296
	ds_read_b128 v[218:221], v133 offset:56320
	global_load_lds_dwordx4 v[146:147], off
	s_add_i32 m0, s58, 0x2000
	s_add_u32 s48, s48, 0x40080
	v_lshl_add_u64 v[146:147], v[154:155], 0, s[0:1]
	s_addc_u32 s49, s49, 0
	s_add_i32 s58, s61, s69
	global_load_lds_dwordx4 v[146:147], off
	v_lshl_add_u64 v[146:147], s[48:49], 0, v[148:149]
	s_mov_b32 m0, s58
	s_nop 0
	global_load_lds_dwordx4 v[146:147], off
	v_lshl_add_u64 v[146:147], s[48:49], 0, v[130:131]
	s_add_i32 m0, s58, 0x2000
	s_nop 0
	global_load_lds_dwordx4 v[146:147], off
	v_lshl_add_u64 v[146:147], v[160:161], 0, s[0:1]
	s_mov_b32 m0, s74
	s_nop 0
	global_load_lds_dwordx4 v[146:147], off
	v_lshl_add_u64 v[146:147], v[208:209], 0, s[0:1]
	s_mov_b32 m0, s75
	s_nop 0
	global_load_lds_dwordx4 v[146:147], off
	s_waitcnt vmcnt(8) lgkmcnt(0)
	s_setprio 1
	s_barrier
	v_mfma_f32_16x16x32_bf16 v[60:63], v[134:137], v[180:183], v[60:63]
	v_mfma_f32_16x16x32_bf16 v[56:59], v[142:145], v[180:183], v[56:59]
	v_mfma_f32_16x16x32_bf16 v[44:47], v[134:137], v[188:191], v[44:47]
	v_mfma_f32_16x16x32_bf16 v[40:43], v[142:145], v[188:191], v[40:43]
	v_mfma_f32_16x16x32_bf16 v[28:31], v[134:137], v[196:199], v[28:31]
	v_mfma_f32_16x16x32_bf16 v[24:27], v[142:145], v[196:199], v[24:27]
	v_mfma_f32_16x16x32_bf16 v[12:15], v[134:137], v[204:207], v[12:15]
	v_mfma_f32_16x16x32_bf16 v[8:11], v[142:145], v[204:207], v[8:11]
	v_mfma_f32_16x16x32_bf16 v[60:63], v[138:141], v[184:187], v[60:63]
	v_mfma_f32_16x16x32_bf16 v[56:59], v[156:159], v[184:187], v[56:59]
	v_mfma_f32_16x16x32_bf16 v[44:47], v[138:141], v[192:195], v[44:47]
	v_mfma_f32_16x16x32_bf16 v[40:43], v[156:159], v[192:195], v[40:43]
	v_mfma_f32_16x16x32_bf16 v[28:31], v[138:141], v[200:203], v[28:31]
	v_mfma_f32_16x16x32_bf16 v[24:27], v[156:159], v[200:203], v[24:27]
	v_mfma_f32_16x16x32_bf16 v[12:15], v[138:141], v[218:221], v[12:15]
	v_mfma_f32_16x16x32_bf16 v[8:11], v[156:159], v[218:221], v[8:11]
	s_setprio 0
	s_setprio 1
	v_mfma_f32_16x16x32_bf16 v[52:55], v[164:167], v[180:183], v[52:55]
	v_mfma_f32_16x16x32_bf16 v[48:51], v[172:175], v[180:183], v[48:51]
	v_mfma_f32_16x16x32_bf16 v[36:39], v[164:167], v[188:191], v[36:39]
	v_mfma_f32_16x16x32_bf16 v[32:35], v[172:175], v[188:191], v[32:35]
	v_mfma_f32_16x16x32_bf16 v[20:23], v[164:167], v[196:199], v[20:23]
	v_mfma_f32_16x16x32_bf16 v[16:19], v[172:175], v[196:199], v[16:19]
	v_mfma_f32_16x16x32_bf16 v[4:7], v[164:167], v[204:207], v[4:7]
	v_mfma_f32_16x16x32_bf16 v[0:3], v[172:175], v[204:207], v[0:3]
	v_mfma_f32_16x16x32_bf16 v[52:55], v[168:171], v[184:187], v[52:55]
	v_mfma_f32_16x16x32_bf16 v[48:51], v[176:179], v[184:187], v[48:51]
	v_mfma_f32_16x16x32_bf16 v[36:39], v[168:171], v[192:195], v[36:39]
	v_mfma_f32_16x16x32_bf16 v[32:35], v[176:179], v[192:195], v[32:35]
	v_mfma_f32_16x16x32_bf16 v[20:23], v[168:171], v[200:203], v[20:23]
	v_mfma_f32_16x16x32_bf16 v[16:19], v[176:179], v[200:203], v[16:19]
	v_mfma_f32_16x16x32_bf16 v[4:7], v[168:171], v[218:221], v[4:7]
	v_mfma_f32_16x16x32_bf16 v[0:3], v[176:179], v[218:221], v[0:3]
	s_barrier
	s_setprio 0
	s_add_i32 s48, s78, 2
	s_cmp_gt_u32 s78, 13
	s_cbranch_scc1 .LBB0_843
	s_mov_b32 s78, s48
	s_branch .LBB0_820

.LBB0_903:
	s_add_u32 s36, s22, s34
	s_addc_u32 s37, s23, s35
	s_add_u32 s36, s36, 0x100
	s_addc_u32 s37, s37, 0
	s_add_u32 s71, s64, s34
	s_addc_u32 s72, s65, s35
	s_add_i32 s73, 0, 0x10000
	s_cmpk_eq_i32 s34, 0x700
	s_cselect_b32 s39, s27, s37
	s_cselect_b32 s38, s68, s36
	v_add_u32_e32 v146, s73, v140
	s_cselect_b32 s37, s25, s72
	s_cselect_b32 s36, s69, s71
	s_add_i32 s71, 0, 0x14000
	ds_read_b128 v[142:145], v146
	ds_read_b128 v[156:159], v146 offset:1024
	ds_read_b128 v[160:163], v146 offset:2048
	ds_read_b128 v[164:167], v146 offset:3072
	v_add_u32_e32 v146, s71, v140
	ds_read_b128 v[168:171], v146
	ds_read_b128 v[172:175], v146 offset:1024
	ds_read_b128 v[176:179], v146 offset:2048
	ds_read_b128 v[184:187], v146 offset:3072
	v_lshl_add_u64 v[146:147], v[138:139], 0, s[34:35]
	s_add_i32 m0, s47, 0xc000
	ds_read_b128 v[188:191], v141
	ds_read_b128 v[192:195], v141 offset:1024
	ds_read_b128 v[196:199], v141 offset:2048
	ds_read_b128 v[200:203], v141 offset:3072
	ds_read_b128 v[204:207], v141 offset:4096
	ds_read_b128 v[218:221], v141 offset:5120
	ds_read_b128 v[222:225], v141 offset:6144
	ds_read_b128 v[226:229], v141 offset:7168
	global_load_lds_dwordx4 v[146:147], off
	v_lshl_add_u64 v[146:147], v[134:135], 0, s[34:35]
	s_add_i32 m0, s47, 0xe000
	s_nop 0
	global_load_lds_dwordx4 v[146:147], off
	s_waitcnt vmcnt(8) lgkmcnt(0)
	s_setprio 1
	s_barrier
	v_mfma_f32_16x16x32_bf16 v[48:51], v[142:145], v[188:191], v[48:51]
	v_mfma_f32_16x16x32_bf16 v[52:55], v[160:163], v[188:191], v[52:55]
	v_mfma_f32_16x16x32_bf16 v[128:131], v[142:145], v[196:199], v[128:131]
	v_mfma_f32_16x16x32_bf16 v[64:67], v[160:163], v[196:199], v[64:67]
	v_mfma_f32_16x16x32_bf16 v[96:99], v[142:145], v[204:207], v[96:99]
	v_mfma_f32_16x16x32_bf16 v[100:103], v[160:163], v[204:207], v[100:103]
	v_mfma_f32_16x16x32_bf16 v[120:123], v[142:145], v[222:225], v[120:123]
	v_mfma_f32_16x16x32_bf16 v[124:127], v[160:163], v[222:225], v[124:127]
	v_mfma_f32_16x16x32_bf16 v[48:51], v[156:159], v[192:195], v[48:51]
	v_mfma_f32_16x16x32_bf16 v[52:55], v[164:167], v[192:195], v[52:55]
	v_mfma_f32_16x16x32_bf16 v[128:131], v[156:159], v[200:203], v[128:131]
	v_mfma_f32_16x16x32_bf16 v[64:67], v[164:167], v[200:203], v[64:67]
	v_mfma_f32_16x16x32_bf16 v[96:99], v[156:159], v[218:221], v[96:99]
	v_mfma_f32_16x16x32_bf16 v[100:103], v[164:167], v[218:221], v[100:103]
	v_mfma_f32_16x16x32_bf16 v[120:123], v[156:159], v[226:229], v[120:123]
	v_mfma_f32_16x16x32_bf16 v[124:127], v[164:167], v[226:229], v[124:127]
	s_setprio 0
	s_setprio 1
	v_mfma_f32_16x16x32_bf16 v[56:59], v[168:171], v[188:191], v[56:59]
	v_mfma_f32_16x16x32_bf16 v[60:63], v[176:179], v[188:191], v[60:63]
	v_mfma_f32_16x16x32_bf16 v[72:75], v[168:171], v[196:199], v[72:75]
	v_mfma_f32_16x16x32_bf16 v[76:79], v[176:179], v[196:199], v[76:79]
	v_mfma_f32_16x16x32_bf16 v[104:107], v[168:171], v[204:207], v[104:107]
	v_mfma_f32_16x16x32_bf16 v[108:111], v[176:179], v[204:207], v[108:111]
	v_mfma_f32_16x16x32_bf16 v[116:119], v[168:171], v[222:225], v[116:119]
	v_mfma_f32_16x16x32_bf16 v[112:115], v[176:179], v[222:225], v[112:115]
	v_mfma_f32_16x16x32_bf16 v[56:59], v[172:175], v[192:195], v[56:59]
	v_mfma_f32_16x16x32_bf16 v[60:63], v[184:187], v[192:195], v[60:63]
	v_mfma_f32_16x16x32_bf16 v[72:75], v[172:175], v[200:203], v[72:75]
	v_mfma_f32_16x16x32_bf16 v[76:79], v[184:187], v[200:203], v[76:79]
	v_mfma_f32_16x16x32_bf16 v[104:107], v[172:175], v[218:221], v[104:107]
	v_mfma_f32_16x16x32_bf16 v[108:111], v[184:187], v[218:221], v[108:111]
	v_mfma_f32_16x16x32_bf16 v[116:119], v[172:175], v[226:229], v[116:119]
	v_mfma_f32_16x16x32_bf16 v[112:115], v[184:187], v[226:229], v[112:115]
	s_barrier
	s_setprio 0
	s_add_i32 s72, s73, s46
	v_lshl_add_u64 v[146:147], s[36:37], 0, v[148:149]
	s_mov_b32 m0, s72
	ds_read_b128 v[188:191], v141 offset:16384
	ds_read_b128 v[192:195], v141 offset:17408
	ds_read_b128 v[196:199], v141 offset:18432
	ds_read_b128 v[200:203], v141 offset:19456
	ds_read_b128 v[204:207], v141 offset:20480
	ds_read_b128 v[218:221], v141 offset:21504
	ds_read_b128 v[222:225], v141 offset:22528
	ds_read_b128 v[226:229], v141 offset:23552
	global_load_lds_dwordx4 v[146:147], off
	s_add_i32 m0, s72, 0x2000
	s_add_u32 s72, s36, 0x40000
	v_lshl_add_u64 v[154:155], s[36:37], 0, v[80:81]
	s_addc_u32 s73, s37, 0
	s_add_i32 s71, s71, s46
	global_load_lds_dwordx4 v[154:155], off
	v_lshl_add_u64 v[180:181], s[72:73], 0, v[148:149]
	s_mov_b32 m0, s71
	v_lshl_add_u64 v[208:209], s[38:39], 0, v[80:81]
	global_load_lds_dwordx4 v[180:181], off
	v_lshl_add_u64 v[180:181], s[72:73], 0, v[80:81]
	s_add_i32 m0, s71, 0x2000
	s_nop 0
	global_load_lds_dwordx4 v[180:181], off
	v_lshl_add_u64 v[180:181], s[38:39], 0, v[148:149]
	s_mov_b32 m0, s47
	s_nop 0
	global_load_lds_dwordx4 v[180:181], off
	s_mov_b32 m0, s49
	s_nop 0
	global_load_lds_dwordx4 v[208:209], off
	s_waitcnt vmcnt(8) lgkmcnt(0)
	s_setprio 1
	s_barrier
	v_mfma_f32_16x16x32_bf16 v[92:95], v[142:145], v[188:191], v[92:95]
	v_mfma_f32_16x16x32_bf16 v[88:91], v[160:163], v[188:191], v[88:91]
	v_mfma_f32_16x16x32_bf16 v[44:47], v[142:145], v[196:199], v[44:47]
	v_mfma_f32_16x16x32_bf16 v[40:43], v[160:163], v[196:199], v[40:43]
	v_mfma_f32_16x16x32_bf16 v[28:31], v[142:145], v[204:207], v[28:31]
	v_mfma_f32_16x16x32_bf16 v[24:27], v[160:163], v[204:207], v[24:27]
	v_mfma_f32_16x16x32_bf16 v[12:15], v[142:145], v[222:225], v[12:15]
	v_mfma_f32_16x16x32_bf16 v[8:11], v[160:163], v[222:225], v[8:11]
	v_mfma_f32_16x16x32_bf16 v[92:95], v[156:159], v[192:195], v[92:95]
	v_mfma_f32_16x16x32_bf16 v[88:91], v[164:167], v[192:195], v[88:91]
	v_mfma_f32_16x16x32_bf16 v[44:47], v[156:159], v[200:203], v[44:47]
	v_mfma_f32_16x16x32_bf16 v[40:43], v[164:167], v[200:203], v[40:43]
	v_mfma_f32_16x16x32_bf16 v[28:31], v[156:159], v[218:221], v[28:31]
	v_mfma_f32_16x16x32_bf16 v[24:27], v[164:167], v[218:221], v[24:27]
	v_mfma_f32_16x16x32_bf16 v[12:15], v[156:159], v[226:229], v[12:15]
	v_mfma_f32_16x16x32_bf16 v[8:11], v[164:167], v[226:229], v[8:11]
	s_setprio 0
	s_setprio 1
	v_mfma_f32_16x16x32_bf16 v[84:87], v[168:171], v[188:191], v[84:87]
	v_mfma_f32_16x16x32_bf16 v[68:71], v[176:179], v[188:191], v[68:71]
	v_mfma_f32_16x16x32_bf16 v[36:39], v[168:171], v[196:199], v[36:39]
	v_mfma_f32_16x16x32_bf16 v[32:35], v[176:179], v[196:199], v[32:35]
	v_mfma_f32_16x16x32_bf16 v[20:23], v[168:171], v[204:207], v[20:23]
	v_mfma_f32_16x16x32_bf16 v[16:19], v[176:179], v[204:207], v[16:19]
	v_mfma_f32_16x16x32_bf16 v[4:7], v[168:171], v[222:225], v[4:7]
	v_mfma_f32_16x16x32_bf16 v[0:3], v[176:179], v[222:225], v[0:3]
	v_mfma_f32_16x16x32_bf16 v[84:87], v[172:175], v[192:195], v[84:87]
	v_mfma_f32_16x16x32_bf16 v[68:71], v[184:187], v[192:195], v[68:71]
	v_mfma_f32_16x16x32_bf16 v[36:39], v[172:175], v[200:203], v[36:39]
	v_mfma_f32_16x16x32_bf16 v[32:35], v[184:187], v[200:203], v[32:35]
	v_mfma_f32_16x16x32_bf16 v[20:23], v[172:175], v[218:221], v[20:23]
	v_mfma_f32_16x16x32_bf16 v[16:19], v[184:187], v[218:221], v[16:19]
	v_mfma_f32_16x16x32_bf16 v[4:7], v[172:175], v[226:229], v[4:7]
	v_mfma_f32_16x16x32_bf16 v[0:3], v[184:187], v[226:229], v[0:3]
	s_barrier
	s_setprio 0
	s_add_i32 s71, 0, 0x18000
	s_add_i32 s72, 0, 0x1c000
	v_add_u32_e32 v164, s71, v140
	v_add_u32_e32 v183, s72, v140
	ds_read_b128 v[142:145], v164
	ds_read_b128 v[156:159], v164 offset:1024
	ds_read_b128 v[160:163], v164 offset:2048
	ds_read_b128 v[164:167], v164 offset:3072
	ds_read_b128 v[168:171], v183
	ds_read_b128 v[172:175], v183 offset:1024
	ds_read_b128 v[176:179], v183 offset:2048
	ds_read_b128 v[184:187], v183 offset:3072
	s_add_u32 s38, s38, 0x40000
	s_addc_u32 s39, s39, 0
	s_mov_b32 m0, s58
	v_lshl_add_u64 v[212:213], s[38:39], 0, v[148:149]
	ds_read_b128 v[188:191], v141 offset:32768
	ds_read_b128 v[192:195], v141 offset:33792
	ds_read_b128 v[196:199], v141 offset:34816
	ds_read_b128 v[200:203], v141 offset:35840
	ds_read_b128 v[204:207], v141 offset:36864
	ds_read_b128 v[218:221], v141 offset:37888
	ds_read_b128 v[222:225], v141 offset:38912
	ds_read_b128 v[226:229], v141 offset:39936
	global_load_lds_dwordx4 v[212:213], off
	v_lshl_add_u64 v[212:213], s[38:39], 0, v[80:81]
	s_mov_b32 m0, s59
	s_nop 0
	global_load_lds_dwordx4 v[212:213], off
	s_waitcnt vmcnt(8) lgkmcnt(0)
	s_setprio 1
	s_barrier
	v_mfma_f32_16x16x32_bf16 v[48:51], v[142:145], v[188:191], v[48:51]
	v_mfma_f32_16x16x32_bf16 v[52:55], v[160:163], v[188:191], v[52:55]
	v_mfma_f32_16x16x32_bf16 v[128:131], v[142:145], v[196:199], v[128:131]
	v_mfma_f32_16x16x32_bf16 v[64:67], v[160:163], v[196:199], v[64:67]
	v_mfma_f32_16x16x32_bf16 v[96:99], v[142:145], v[204:207], v[96:99]
	v_mfma_f32_16x16x32_bf16 v[100:103], v[160:163], v[204:207], v[100:103]
	v_mfma_f32_16x16x32_bf16 v[120:123], v[142:145], v[222:225], v[120:123]
	v_mfma_f32_16x16x32_bf16 v[124:127], v[160:163], v[222:225], v[124:127]
	v_mfma_f32_16x16x32_bf16 v[48:51], v[156:159], v[192:195], v[48:51]
	v_mfma_f32_16x16x32_bf16 v[52:55], v[164:167], v[192:195], v[52:55]
	v_mfma_f32_16x16x32_bf16 v[128:131], v[156:159], v[200:203], v[128:131]
	v_mfma_f32_16x16x32_bf16 v[64:67], v[164:167], v[200:203], v[64:67]
	v_mfma_f32_16x16x32_bf16 v[96:99], v[156:159], v[218:221], v[96:99]
	v_mfma_f32_16x16x32_bf16 v[100:103], v[164:167], v[218:221], v[100:103]
	v_mfma_f32_16x16x32_bf16 v[120:123], v[156:159], v[226:229], v[120:123]
	v_mfma_f32_16x16x32_bf16 v[124:127], v[164:167], v[226:229], v[124:127]
	s_setprio 0
	s_setprio 1
	v_mfma_f32_16x16x32_bf16 v[56:59], v[168:171], v[188:191], v[56:59]
	v_mfma_f32_16x16x32_bf16 v[60:63], v[176:179], v[188:191], v[60:63]
	v_mfma_f32_16x16x32_bf16 v[72:75], v[168:171], v[196:199], v[72:75]
	v_mfma_f32_16x16x32_bf16 v[76:79], v[176:179], v[196:199], v[76:79]
	v_mfma_f32_16x16x32_bf16 v[104:107], v[168:171], v[204:207], v[104:107]
	v_mfma_f32_16x16x32_bf16 v[108:111], v[176:179], v[204:207], v[108:111]
	v_mfma_f32_16x16x32_bf16 v[116:119], v[168:171], v[222:225], v[116:119]
	v_mfma_f32_16x16x32_bf16 v[112:115], v[176:179], v[222:225], v[112:115]
	v_mfma_f32_16x16x32_bf16 v[56:59], v[172:175], v[192:195], v[56:59]
	v_mfma_f32_16x16x32_bf16 v[60:63], v[184:187], v[192:195], v[60:63]
	v_mfma_f32_16x16x32_bf16 v[72:75], v[172:175], v[200:203], v[72:75]
	v_mfma_f32_16x16x32_bf16 v[76:79], v[184:187], v[200:203], v[76:79]
	v_mfma_f32_16x16x32_bf16 v[104:107], v[172:175], v[218:221], v[104:107]
	v_mfma_f32_16x16x32_bf16 v[108:111], v[184:187], v[218:221], v[108:111]
	v_mfma_f32_16x16x32_bf16 v[116:119], v[172:175], v[226:229], v[116:119]
	v_mfma_f32_16x16x32_bf16 v[112:115], v[184:187], v[226:229], v[112:115]
	s_barrier
	s_setprio 0
	s_add_i32 s38, s71, s46
	v_lshl_add_u64 v[146:147], v[146:147], 0, s[0:1]
	s_mov_b32 m0, s38
	ds_read_b128 v[188:191], v141 offset:49152
	ds_read_b128 v[192:195], v141 offset:50176
	ds_read_b128 v[196:199], v141 offset:51200
	ds_read_b128 v[200:203], v141 offset:52224
	ds_read_b128 v[204:207], v141 offset:53248
	ds_read_b128 v[218:221], v141 offset:54272
	ds_read_b128 v[222:225], v141 offset:55296
	ds_read_b128 v[226:229], v141 offset:56320
	global_load_lds_dwordx4 v[146:147], off
	s_add_i32 m0, s38, 0x2000
	s_add_u32 s36, s36, 0x40080
	v_lshl_add_u64 v[146:147], v[154:155], 0, s[0:1]
	s_addc_u32 s37, s37, 0
	s_add_i32 s38, s72, s46
	global_load_lds_dwordx4 v[146:147], off
	v_lshl_add_u64 v[146:147], s[36:37], 0, v[148:149]
	s_mov_b32 m0, s38
	s_nop 0
	global_load_lds_dwordx4 v[146:147], off
	v_lshl_add_u64 v[146:147], s[36:37], 0, v[80:81]
	s_add_i32 m0, s38, 0x2000
	s_nop 0
	global_load_lds_dwordx4 v[146:147], off
	v_lshl_add_u64 v[146:147], v[180:181], 0, s[0:1]
	s_mov_b32 m0, s60
	s_nop 0
	global_load_lds_dwordx4 v[146:147], off
	v_lshl_add_u64 v[146:147], v[208:209], 0, s[0:1]
	s_mov_b32 m0, s61
	s_nop 0
	global_load_lds_dwordx4 v[146:147], off
	s_waitcnt vmcnt(8) lgkmcnt(0)
	s_setprio 1
	s_barrier
	v_mfma_f32_16x16x32_bf16 v[92:95], v[142:145], v[188:191], v[92:95]
	v_mfma_f32_16x16x32_bf16 v[88:91], v[160:163], v[188:191], v[88:91]
	v_mfma_f32_16x16x32_bf16 v[44:47], v[142:145], v[196:199], v[44:47]
	v_mfma_f32_16x16x32_bf16 v[40:43], v[160:163], v[196:199], v[40:43]
	v_mfma_f32_16x16x32_bf16 v[28:31], v[142:145], v[204:207], v[28:31]
	v_mfma_f32_16x16x32_bf16 v[24:27], v[160:163], v[204:207], v[24:27]
	v_mfma_f32_16x16x32_bf16 v[12:15], v[142:145], v[222:225], v[12:15]
	v_mfma_f32_16x16x32_bf16 v[8:11], v[160:163], v[222:225], v[8:11]
	v_mfma_f32_16x16x32_bf16 v[92:95], v[156:159], v[192:195], v[92:95]
	v_mfma_f32_16x16x32_bf16 v[88:91], v[164:167], v[192:195], v[88:91]
	v_mfma_f32_16x16x32_bf16 v[44:47], v[156:159], v[200:203], v[44:47]
	v_mfma_f32_16x16x32_bf16 v[40:43], v[164:167], v[200:203], v[40:43]
	v_mfma_f32_16x16x32_bf16 v[28:31], v[156:159], v[218:221], v[28:31]
	v_mfma_f32_16x16x32_bf16 v[24:27], v[164:167], v[218:221], v[24:27]
	v_mfma_f32_16x16x32_bf16 v[12:15], v[156:159], v[226:229], v[12:15]
	v_mfma_f32_16x16x32_bf16 v[8:11], v[164:167], v[226:229], v[8:11]
	s_setprio 0
	s_setprio 1
	v_mfma_f32_16x16x32_bf16 v[84:87], v[168:171], v[188:191], v[84:87]
	v_mfma_f32_16x16x32_bf16 v[68:71], v[176:179], v[188:191], v[68:71]
	v_mfma_f32_16x16x32_bf16 v[36:39], v[168:171], v[196:199], v[36:39]
	v_mfma_f32_16x16x32_bf16 v[32:35], v[176:179], v[196:199], v[32:35]
	v_mfma_f32_16x16x32_bf16 v[20:23], v[168:171], v[204:207], v[20:23]
	v_mfma_f32_16x16x32_bf16 v[16:19], v[176:179], v[204:207], v[16:19]
	v_mfma_f32_16x16x32_bf16 v[4:7], v[168:171], v[222:225], v[4:7]
	v_mfma_f32_16x16x32_bf16 v[0:3], v[176:179], v[222:225], v[0:3]
	v_mfma_f32_16x16x32_bf16 v[84:87], v[172:175], v[192:195], v[84:87]
	v_mfma_f32_16x16x32_bf16 v[68:71], v[184:187], v[192:195], v[68:71]
	v_mfma_f32_16x16x32_bf16 v[36:39], v[172:175], v[200:203], v[36:39]
	v_mfma_f32_16x16x32_bf16 v[32:35], v[184:187], v[200:203], v[32:35]
	v_mfma_f32_16x16x32_bf16 v[20:23], v[172:175], v[218:221], v[20:23]
	v_mfma_f32_16x16x32_bf16 v[16:19], v[184:187], v[218:221], v[16:19]
	v_mfma_f32_16x16x32_bf16 v[4:7], v[172:175], v[226:229], v[4:7]
	v_mfma_f32_16x16x32_bf16 v[0:3], v[184:187], v[226:229], v[0:3]
	s_barrier
	s_setprio 0
	s_add_i32 s70, s70, 2
	s_add_u32 s34, s34, 0x100
	s_addc_u32 s35, s35, 0
	s_cmp_gt_u32 s70, 13
	s_cbranch_scc0 .LBB0_903
	s_add_u32 s34, s64, 0xffffff00
	s_addc_u32 s35, s65, -1
	s_andn2_b64 vcc, exec, s[44:45]
	s_cbranch_vccnz .LBB0_906
	v_mov_b32_e32 v0, 0
	s_mov_b32 s6, s24
	s_mov_b32 s4, s26
	s_mov_b64 s[22:23], s[30:31]
	s_mov_b32 s62, s63
	v_mov_b32_e32 v1, v0
	v_mov_b32_e32 v2, v0
	v_mov_b32_e32 v3, v0
	v_mov_b32_e32 v4, v0
	v_mov_b32_e32 v5, v0
	v_mov_b32_e32 v6, v0
	v_mov_b32_e32 v7, v0
	v_mov_b32_e32 v16, v0
	v_mov_b32_e32 v17, v0
	v_mov_b32_e32 v18, v0
	v_mov_b32_e32 v19, v0
	v_mov_b32_e32 v20, v0
	v_mov_b32_e32 v21, v0
	v_mov_b32_e32 v22, v0
	v_mov_b32_e32 v23, v0
	v_mov_b32_e32 v32, v0
	v_mov_b32_e32 v33, v0
	v_mov_b32_e32 v34, v0
	v_mov_b32_e32 v35, v0
	v_mov_b32_e32 v36, v0
	v_mov_b32_e32 v37, v0
	v_mov_b32_e32 v38, v0
	v_mov_b32_e32 v39, v0
	v_mov_b32_e32 v68, v0
	v_mov_b32_e32 v69, v0
	v_mov_b32_e32 v70, v0
	v_mov_b32_e32 v71, v0
	v_mov_b32_e32 v84, v0
	v_mov_b32_e32 v85, v0
	v_mov_b32_e32 v86, v0
	v_mov_b32_e32 v87, v0
	v_mov_b32_e32 v8, v0
	v_mov_b32_e32 v9, v0
	v_mov_b32_e32 v10, v0
	v_mov_b32_e32 v11, v0
	v_mov_b32_e32 v12, v0
	v_mov_b32_e32 v13, v0
	v_mov_b32_e32 v14, v0
	v_mov_b32_e32 v15, v0
	v_mov_b32_e32 v24, v0
	v_mov_b32_e32 v25, v0
	v_mov_b32_e32 v26, v0
	v_mov_b32_e32 v27, v0
	v_mov_b32_e32 v28, v0
	v_mov_b32_e32 v29, v0
	v_mov_b32_e32 v30, v0
	v_mov_b32_e32 v31, v0
	v_mov_b32_e32 v40, v0
	v_mov_b32_e32 v41, v0
	v_mov_b32_e32 v42, v0
	v_mov_b32_e32 v43, v0
	v_mov_b32_e32 v44, v0
	v_mov_b32_e32 v45, v0
	v_mov_b32_e32 v46, v0
	v_mov_b32_e32 v47, v0
	v_mov_b32_e32 v88, v0
	v_mov_b32_e32 v89, v0
	v_mov_b32_e32 v90, v0
	v_mov_b32_e32 v91, v0
	v_mov_b32_e32 v92, v0
	v_mov_b32_e32 v93, v0
	v_mov_b32_e32 v94, v0
	v_mov_b32_e32 v95, v0
	v_mov_b32_e32 v112, v0
	v_mov_b32_e32 v113, v0
	v_mov_b32_e32 v114, v0
	v_mov_b32_e32 v115, v0
	v_mov_b32_e32 v116, v0
	v_mov_b32_e32 v117, v0
	v_mov_b32_e32 v118, v0
	v_mov_b32_e32 v119, v0
	v_mov_b32_e32 v108, v0
	v_mov_b32_e32 v109, v0
	v_mov_b32_e32 v110, v0
	v_mov_b32_e32 v111, v0
	v_mov_b32_e32 v104, v0
	v_mov_b32_e32 v105, v0
	v_mov_b32_e32 v106, v0
	v_mov_b32_e32 v107, v0
	v_mov_b32_e32 v76, v0
	v_mov_b32_e32 v77, v0
	v_mov_b32_e32 v78, v0
	v_mov_b32_e32 v79, v0
	v_mov_b32_e32 v72, v0
	v_mov_b32_e32 v73, v0
	v_mov_b32_e32 v74, v0
	v_mov_b32_e32 v75, v0
	v_mov_b32_e32 v60, v0
	v_mov_b32_e32 v61, v0
	v_mov_b32_e32 v62, v0
	v_mov_b32_e32 v63, v0
	v_mov_b32_e32 v56, v0
	v_mov_b32_e32 v57, v0
	v_mov_b32_e32 v58, v0
	v_mov_b32_e32 v59, v0
	v_mov_b32_e32 v124, v0
	v_mov_b32_e32 v125, v0
	v_mov_b32_e32 v126, v0
	v_mov_b32_e32 v127, v0
	v_mov_b32_e32 v120, v0
	v_mov_b32_e32 v121, v0
	v_mov_b32_e32 v122, v0
	v_mov_b32_e32 v123, v0
	v_mov_b32_e32 v100, v0
	v_mov_b32_e32 v101, v0
	v_mov_b32_e32 v102, v0
	v_mov_b32_e32 v103, v0
	v_mov_b32_e32 v96, v0
	v_mov_b32_e32 v97, v0
	v_mov_b32_e32 v98, v0
	v_mov_b32_e32 v99, v0
	v_mov_b32_e32 v64, v0
	v_mov_b32_e32 v65, v0
	v_mov_b32_e32 v66, v0
	v_mov_b32_e32 v67, v0
	v_mov_b32_e32 v128, v0
	v_mov_b32_e32 v129, v0
	v_mov_b32_e32 v130, v0
	v_mov_b32_e32 v131, v0
	v_mov_b32_e32 v52, v0
	v_mov_b32_e32 v53, v0
	v_mov_b32_e32 v54, v0
	v_mov_b32_e32 v55, v0
	v_mov_b32_e32 v48, v0
	v_mov_b32_e32 v49, v0
	v_mov_b32_e32 v50, v0
	v_mov_b32_e32 v51, v0
	s_andn2_b64 vcc, exec, s[42:43]
	s_cbranch_vccnz .LBB0_907
	s_branch .LBB0_908

.LBB0_985:
	s_add_u32 s24, s44, s22
	s_addc_u32 s25, s45, s23
	s_add_u32 s24, s24, 0x3e00100
	s_addc_u32 s25, s25, 0
	s_add_u32 s47, s42, s22
	s_addc_u32 s48, s43, s23
	s_add_i32 s49, 0, 0x10000
	s_cmpk_eq_i32 s22, 0x700
	s_cselect_b32 s27, s7, s25
	s_cselect_b32 s26, s6, s24
	v_add_u32_e32 v137, s49, v135
	s_cselect_b32 s25, s5, s48
	s_cselect_b32 s24, s4, s47
	s_add_i32 s47, 0, 0x14000
	ds_read_b128 v[138:141], v137
	ds_read_b128 v[142:145], v137 offset:1024
	ds_read_b128 v[156:159], v137 offset:2048
	ds_read_b128 v[162:165], v137 offset:3072
	v_add_u32_e32 v137, s47, v135
	ds_read_b128 v[166:169], v137
	ds_read_b128 v[170:173], v137 offset:1024
	ds_read_b128 v[176:179], v137 offset:2048
	ds_read_b128 v[180:183], v137 offset:3072
	v_lshl_add_u64 v[146:147], v[132:133], 0, s[22:23]
	s_add_i32 m0, s34, 0xc000
	ds_read_b128 v[184:187], v136
	ds_read_b128 v[188:191], v136 offset:1024
	ds_read_b128 v[192:195], v136 offset:2048
	ds_read_b128 v[196:199], v136 offset:3072
	ds_read_b128 v[200:203], v136 offset:4096
	ds_read_b128 v[204:207], v136 offset:5120
	ds_read_b128 v[218:221], v136 offset:6144
	ds_read_b128 v[222:225], v136 offset:7168
	global_load_lds_dwordx4 v[146:147], off
	v_lshl_add_u64 v[146:147], v[130:131], 0, s[22:23]
	s_add_i32 m0, s34, 0xe000
	s_nop 0
	global_load_lds_dwordx4 v[146:147], off
	s_waitcnt vmcnt(8) lgkmcnt(0)
	s_setprio 1
	s_barrier
	v_mfma_f32_16x16x32_bf16 v[16:19], v[138:141], v[184:187], v[16:19]
	v_mfma_f32_16x16x32_bf16 v[20:23], v[156:159], v[184:187], v[20:23]
	v_mfma_f32_16x16x32_bf16 v[36:39], v[138:141], v[192:195], v[36:39]
	v_mfma_f32_16x16x32_bf16 v[40:43], v[156:159], v[192:195], v[40:43]
	v_mfma_f32_16x16x32_bf16 v[64:67], v[138:141], v[200:203], v[64:67]
	v_mfma_f32_16x16x32_bf16 v[68:71], v[156:159], v[200:203], v[68:71]
	v_mfma_f32_16x16x32_bf16 v[96:99], v[138:141], v[218:221], v[96:99]
	v_mfma_f32_16x16x32_bf16 v[100:103], v[156:159], v[218:221], v[100:103]
	v_mfma_f32_16x16x32_bf16 v[16:19], v[142:145], v[188:191], v[16:19]
	v_mfma_f32_16x16x32_bf16 v[20:23], v[162:165], v[188:191], v[20:23]
	v_mfma_f32_16x16x32_bf16 v[36:39], v[142:145], v[196:199], v[36:39]
	v_mfma_f32_16x16x32_bf16 v[40:43], v[162:165], v[196:199], v[40:43]
	v_mfma_f32_16x16x32_bf16 v[64:67], v[142:145], v[204:207], v[64:67]
	v_mfma_f32_16x16x32_bf16 v[68:71], v[162:165], v[204:207], v[68:71]
	v_mfma_f32_16x16x32_bf16 v[96:99], v[142:145], v[222:225], v[96:99]
	v_mfma_f32_16x16x32_bf16 v[100:103], v[162:165], v[222:225], v[100:103]
	s_setprio 0
	s_setprio 1
	v_mfma_f32_16x16x32_bf16 v[24:27], v[166:169], v[184:187], v[24:27]
	v_mfma_f32_16x16x32_bf16 v[52:55], v[176:179], v[184:187], v[52:55]
	v_mfma_f32_16x16x32_bf16 v[44:47], v[166:169], v[192:195], v[44:47]
	v_mfma_f32_16x16x32_bf16 v[56:59], v[176:179], v[192:195], v[56:59]
	v_mfma_f32_16x16x32_bf16 v[72:75], v[166:169], v[200:203], v[72:75]
	v_mfma_f32_16x16x32_bf16 v[80:83], v[176:179], v[200:203], v[80:83]
	v_mfma_f32_16x16x32_bf16 v[104:107], v[166:169], v[218:221], v[104:107]
	v_mfma_f32_16x16x32_bf16 v[108:111], v[176:179], v[218:221], v[108:111]
	v_mfma_f32_16x16x32_bf16 v[24:27], v[170:173], v[188:191], v[24:27]
	v_mfma_f32_16x16x32_bf16 v[52:55], v[180:183], v[188:191], v[52:55]
	v_mfma_f32_16x16x32_bf16 v[44:47], v[170:173], v[196:199], v[44:47]
	v_mfma_f32_16x16x32_bf16 v[56:59], v[180:183], v[196:199], v[56:59]
	v_mfma_f32_16x16x32_bf16 v[72:75], v[170:173], v[204:207], v[72:75]
	v_mfma_f32_16x16x32_bf16 v[80:83], v[180:183], v[204:207], v[80:83]
	v_mfma_f32_16x16x32_bf16 v[104:107], v[170:173], v[222:225], v[104:107]
	v_mfma_f32_16x16x32_bf16 v[108:111], v[180:183], v[222:225], v[108:111]
	s_barrier
	s_setprio 0
	s_add_i32 s48, s49, s31
	v_lshl_add_u64 v[146:147], s[24:25], 0, v[148:149]
	s_mov_b32 m0, s48
	ds_read_b128 v[184:187], v136 offset:16384
	ds_read_b128 v[188:191], v136 offset:17408
	ds_read_b128 v[192:195], v136 offset:18432
	ds_read_b128 v[196:199], v136 offset:19456
	ds_read_b128 v[200:203], v136 offset:20480
	ds_read_b128 v[204:207], v136 offset:21504
	ds_read_b128 v[218:221], v136 offset:22528
	ds_read_b128 v[222:225], v136 offset:23552
	global_load_lds_dwordx4 v[146:147], off
	s_add_i32 m0, s48, 0x2000
	s_add_u32 s48, s24, 0x40000
	v_lshl_add_u64 v[154:155], s[24:25], 0, v[128:129]
	s_addc_u32 s49, s25, 0
	s_add_i32 s47, s47, s31
	global_load_lds_dwordx4 v[154:155], off
	v_lshl_add_u64 v[208:209], s[48:49], 0, v[148:149]
	s_mov_b32 m0, s47
	v_lshl_add_u64 v[212:213], s[26:27], 0, v[128:129]
	global_load_lds_dwordx4 v[208:209], off
	v_lshl_add_u64 v[208:209], s[48:49], 0, v[128:129]
	s_add_i32 m0, s47, 0x2000
	s_nop 0
	global_load_lds_dwordx4 v[208:209], off
	v_lshl_add_u64 v[208:209], s[26:27], 0, v[148:149]
	s_mov_b32 m0, s34
	s_nop 0
	global_load_lds_dwordx4 v[208:209], off
	s_mov_b32 m0, s35
	s_nop 0
	global_load_lds_dwordx4 v[212:213], off
	s_waitcnt vmcnt(8) lgkmcnt(0)
	s_setprio 1
	s_barrier
	v_mfma_f32_16x16x32_bf16 v[124:127], v[138:141], v[184:187], v[124:127]
	v_mfma_f32_16x16x32_bf16 v[120:123], v[156:159], v[184:187], v[120:123]
	v_mfma_f32_16x16x32_bf16 v[92:95], v[138:141], v[192:195], v[92:95]
	v_mfma_f32_16x16x32_bf16 v[88:91], v[156:159], v[192:195], v[88:91]
	v_mfma_f32_16x16x32_bf16 v[60:63], v[138:141], v[200:203], v[60:63]
	v_mfma_f32_16x16x32_bf16 v[48:51], v[156:159], v[200:203], v[48:51]
	v_mfma_f32_16x16x32_bf16 v[12:15], v[138:141], v[218:221], v[12:15]
	v_mfma_f32_16x16x32_bf16 v[8:11], v[156:159], v[218:221], v[8:11]
	v_mfma_f32_16x16x32_bf16 v[124:127], v[142:145], v[188:191], v[124:127]
	v_mfma_f32_16x16x32_bf16 v[120:123], v[162:165], v[188:191], v[120:123]
	v_mfma_f32_16x16x32_bf16 v[92:95], v[142:145], v[196:199], v[92:95]
	v_mfma_f32_16x16x32_bf16 v[88:91], v[162:165], v[196:199], v[88:91]
	v_mfma_f32_16x16x32_bf16 v[60:63], v[142:145], v[204:207], v[60:63]
	v_mfma_f32_16x16x32_bf16 v[48:51], v[162:165], v[204:207], v[48:51]
	v_mfma_f32_16x16x32_bf16 v[12:15], v[142:145], v[222:225], v[12:15]
	v_mfma_f32_16x16x32_bf16 v[8:11], v[162:165], v[222:225], v[8:11]
	s_setprio 0
	s_setprio 1
	v_mfma_f32_16x16x32_bf16 v[116:119], v[166:169], v[184:187], v[116:119]
	v_mfma_f32_16x16x32_bf16 v[112:115], v[176:179], v[184:187], v[112:115]
	v_mfma_f32_16x16x32_bf16 v[84:87], v[166:169], v[192:195], v[84:87]
	v_mfma_f32_16x16x32_bf16 v[76:79], v[176:179], v[192:195], v[76:79]
	v_mfma_f32_16x16x32_bf16 v[32:35], v[166:169], v[200:203], v[32:35]
	v_mfma_f32_16x16x32_bf16 v[28:31], v[176:179], v[200:203], v[28:31]
	v_mfma_f32_16x16x32_bf16 v[4:7], v[166:169], v[218:221], v[4:7]
	v_mfma_f32_16x16x32_bf16 v[0:3], v[176:179], v[218:221], v[0:3]
	v_mfma_f32_16x16x32_bf16 v[116:119], v[170:173], v[188:191], v[116:119]
	v_mfma_f32_16x16x32_bf16 v[112:115], v[180:183], v[188:191], v[112:115]
	v_mfma_f32_16x16x32_bf16 v[84:87], v[170:173], v[196:199], v[84:87]
	v_mfma_f32_16x16x32_bf16 v[76:79], v[180:183], v[196:199], v[76:79]
	v_mfma_f32_16x16x32_bf16 v[32:35], v[170:173], v[204:207], v[32:35]
	v_mfma_f32_16x16x32_bf16 v[28:31], v[180:183], v[204:207], v[28:31]
	v_mfma_f32_16x16x32_bf16 v[4:7], v[170:173], v[222:225], v[4:7]
	v_mfma_f32_16x16x32_bf16 v[0:3], v[180:183], v[222:225], v[0:3]
	s_barrier
	s_setprio 0
	s_add_i32 s47, 0, 0x18000
	v_add_u32_e32 v137, s47, v135
	s_add_i32 s48, 0, 0x1c000
	ds_read_b128 v[138:141], v137
	ds_read_b128 v[142:145], v137 offset:1024
	ds_read_b128 v[156:159], v137 offset:2048
	ds_read_b128 v[162:165], v137 offset:3072
	v_add_u32_e32 v137, s48, v135
	ds_read_b128 v[166:169], v137
	ds_read_b128 v[170:173], v137 offset:1024
	ds_read_b128 v[176:179], v137 offset:2048
	ds_read_b128 v[180:183], v137 offset:3072
	s_add_u32 s26, s26, 0x40000
	s_addc_u32 s27, s27, 0
	s_mov_b32 m0, s36
	v_lshl_add_u64 v[226:227], s[26:27], 0, v[148:149]
	ds_read_b128 v[184:187], v136 offset:32768
	ds_read_b128 v[188:191], v136 offset:33792
	ds_read_b128 v[192:195], v136 offset:34816
	ds_read_b128 v[196:199], v136 offset:35840
	ds_read_b128 v[200:203], v136 offset:36864
	ds_read_b128 v[204:207], v136 offset:37888
	ds_read_b128 v[218:221], v136 offset:38912
	ds_read_b128 v[222:225], v136 offset:39936
	global_load_lds_dwordx4 v[226:227], off
	v_lshl_add_u64 v[226:227], s[26:27], 0, v[128:129]
	s_mov_b32 m0, s37
	s_nop 0
	global_load_lds_dwordx4 v[226:227], off
	s_waitcnt vmcnt(8) lgkmcnt(0)
	s_setprio 1
	s_barrier
	v_mfma_f32_16x16x32_bf16 v[16:19], v[138:141], v[184:187], v[16:19]
	v_mfma_f32_16x16x32_bf16 v[20:23], v[156:159], v[184:187], v[20:23]
	v_mfma_f32_16x16x32_bf16 v[36:39], v[138:141], v[192:195], v[36:39]
	v_mfma_f32_16x16x32_bf16 v[40:43], v[156:159], v[192:195], v[40:43]
	v_mfma_f32_16x16x32_bf16 v[64:67], v[138:141], v[200:203], v[64:67]
	v_mfma_f32_16x16x32_bf16 v[68:71], v[156:159], v[200:203], v[68:71]
	v_mfma_f32_16x16x32_bf16 v[96:99], v[138:141], v[218:221], v[96:99]
	v_mfma_f32_16x16x32_bf16 v[100:103], v[156:159], v[218:221], v[100:103]
	v_mfma_f32_16x16x32_bf16 v[16:19], v[142:145], v[188:191], v[16:19]
	v_mfma_f32_16x16x32_bf16 v[20:23], v[162:165], v[188:191], v[20:23]
	v_mfma_f32_16x16x32_bf16 v[36:39], v[142:145], v[196:199], v[36:39]
	v_mfma_f32_16x16x32_bf16 v[40:43], v[162:165], v[196:199], v[40:43]
	v_mfma_f32_16x16x32_bf16 v[64:67], v[142:145], v[204:207], v[64:67]
	v_mfma_f32_16x16x32_bf16 v[68:71], v[162:165], v[204:207], v[68:71]
	v_mfma_f32_16x16x32_bf16 v[96:99], v[142:145], v[222:225], v[96:99]
	v_mfma_f32_16x16x32_bf16 v[100:103], v[162:165], v[222:225], v[100:103]
	s_setprio 0
	s_setprio 1
	v_mfma_f32_16x16x32_bf16 v[24:27], v[166:169], v[184:187], v[24:27]
	v_mfma_f32_16x16x32_bf16 v[52:55], v[176:179], v[184:187], v[52:55]
	v_mfma_f32_16x16x32_bf16 v[44:47], v[166:169], v[192:195], v[44:47]
	v_mfma_f32_16x16x32_bf16 v[56:59], v[176:179], v[192:195], v[56:59]
	v_mfma_f32_16x16x32_bf16 v[72:75], v[166:169], v[200:203], v[72:75]
	v_mfma_f32_16x16x32_bf16 v[80:83], v[176:179], v[200:203], v[80:83]
	v_mfma_f32_16x16x32_bf16 v[104:107], v[166:169], v[218:221], v[104:107]
	v_mfma_f32_16x16x32_bf16 v[108:111], v[176:179], v[218:221], v[108:111]
	v_mfma_f32_16x16x32_bf16 v[24:27], v[170:173], v[188:191], v[24:27]
	v_mfma_f32_16x16x32_bf16 v[52:55], v[180:183], v[188:191], v[52:55]
	v_mfma_f32_16x16x32_bf16 v[44:47], v[170:173], v[196:199], v[44:47]
	v_mfma_f32_16x16x32_bf16 v[56:59], v[180:183], v[196:199], v[56:59]
	v_mfma_f32_16x16x32_bf16 v[72:75], v[170:173], v[204:207], v[72:75]
	v_mfma_f32_16x16x32_bf16 v[80:83], v[180:183], v[204:207], v[80:83]
	v_mfma_f32_16x16x32_bf16 v[104:107], v[170:173], v[222:225], v[104:107]
	v_mfma_f32_16x16x32_bf16 v[108:111], v[180:183], v[222:225], v[108:111]
	s_barrier
	s_setprio 0
	s_add_i32 s26, s47, s31
	v_lshl_add_u64 v[146:147], v[146:147], 0, s[0:1]
	s_mov_b32 m0, s26
	ds_read_b128 v[184:187], v136 offset:49152
	ds_read_b128 v[188:191], v136 offset:50176
	ds_read_b128 v[192:195], v136 offset:51200
	ds_read_b128 v[196:199], v136 offset:52224
	ds_read_b128 v[200:203], v136 offset:53248
	ds_read_b128 v[204:207], v136 offset:54272
	ds_read_b128 v[218:221], v136 offset:55296
	ds_read_b128 v[222:225], v136 offset:56320
	global_load_lds_dwordx4 v[146:147], off
	s_add_i32 m0, s26, 0x2000
	s_add_u32 s24, s24, 0x40080
	v_lshl_add_u64 v[146:147], v[154:155], 0, s[0:1]
	s_addc_u32 s25, s25, 0
	s_add_i32 s26, s48, s31
	global_load_lds_dwordx4 v[146:147], off
	v_lshl_add_u64 v[146:147], s[24:25], 0, v[148:149]
	s_mov_b32 m0, s26
	s_nop 0
	global_load_lds_dwordx4 v[146:147], off
	v_lshl_add_u64 v[146:147], s[24:25], 0, v[128:129]
	s_add_i32 m0, s26, 0x2000
	s_nop 0
	global_load_lds_dwordx4 v[146:147], off
	v_lshl_add_u64 v[146:147], v[208:209], 0, s[0:1]
	s_mov_b32 m0, s38
	s_nop 0
	global_load_lds_dwordx4 v[146:147], off
	v_lshl_add_u64 v[146:147], v[212:213], 0, s[0:1]
	s_mov_b32 m0, s39
	s_nop 0
	global_load_lds_dwordx4 v[146:147], off
	s_waitcnt vmcnt(8) lgkmcnt(0)
	s_setprio 1
	s_barrier
	v_mfma_f32_16x16x32_bf16 v[124:127], v[138:141], v[184:187], v[124:127]
	v_mfma_f32_16x16x32_bf16 v[120:123], v[156:159], v[184:187], v[120:123]
	v_mfma_f32_16x16x32_bf16 v[92:95], v[138:141], v[192:195], v[92:95]
	v_mfma_f32_16x16x32_bf16 v[88:91], v[156:159], v[192:195], v[88:91]
	v_mfma_f32_16x16x32_bf16 v[60:63], v[138:141], v[200:203], v[60:63]
	v_mfma_f32_16x16x32_bf16 v[48:51], v[156:159], v[200:203], v[48:51]
	v_mfma_f32_16x16x32_bf16 v[12:15], v[138:141], v[218:221], v[12:15]
	v_mfma_f32_16x16x32_bf16 v[8:11], v[156:159], v[218:221], v[8:11]
	v_mfma_f32_16x16x32_bf16 v[124:127], v[142:145], v[188:191], v[124:127]
	v_mfma_f32_16x16x32_bf16 v[120:123], v[162:165], v[188:191], v[120:123]
	v_mfma_f32_16x16x32_bf16 v[92:95], v[142:145], v[196:199], v[92:95]
	v_mfma_f32_16x16x32_bf16 v[88:91], v[162:165], v[196:199], v[88:91]
	v_mfma_f32_16x16x32_bf16 v[60:63], v[142:145], v[204:207], v[60:63]
	v_mfma_f32_16x16x32_bf16 v[48:51], v[162:165], v[204:207], v[48:51]
	v_mfma_f32_16x16x32_bf16 v[12:15], v[142:145], v[222:225], v[12:15]
	v_mfma_f32_16x16x32_bf16 v[8:11], v[162:165], v[222:225], v[8:11]
	s_setprio 0
	s_setprio 1
	v_mfma_f32_16x16x32_bf16 v[116:119], v[166:169], v[184:187], v[116:119]
	v_mfma_f32_16x16x32_bf16 v[112:115], v[176:179], v[184:187], v[112:115]
	v_mfma_f32_16x16x32_bf16 v[84:87], v[166:169], v[192:195], v[84:87]
	v_mfma_f32_16x16x32_bf16 v[76:79], v[176:179], v[192:195], v[76:79]
	v_mfma_f32_16x16x32_bf16 v[32:35], v[166:169], v[200:203], v[32:35]
	v_mfma_f32_16x16x32_bf16 v[28:31], v[176:179], v[200:203], v[28:31]
	v_mfma_f32_16x16x32_bf16 v[4:7], v[166:169], v[218:221], v[4:7]
	v_mfma_f32_16x16x32_bf16 v[0:3], v[176:179], v[218:221], v[0:3]
	v_mfma_f32_16x16x32_bf16 v[116:119], v[170:173], v[188:191], v[116:119]
	v_mfma_f32_16x16x32_bf16 v[112:115], v[180:183], v[188:191], v[112:115]
	v_mfma_f32_16x16x32_bf16 v[84:87], v[170:173], v[196:199], v[84:87]
	v_mfma_f32_16x16x32_bf16 v[76:79], v[180:183], v[196:199], v[76:79]
	v_mfma_f32_16x16x32_bf16 v[32:35], v[170:173], v[204:207], v[32:35]
	v_mfma_f32_16x16x32_bf16 v[28:31], v[180:183], v[204:207], v[28:31]
	v_mfma_f32_16x16x32_bf16 v[4:7], v[170:173], v[222:225], v[4:7]
	v_mfma_f32_16x16x32_bf16 v[0:3], v[180:183], v[222:225], v[0:3]
	s_barrier
	s_setprio 0
	s_add_i32 s46, s46, 2
	s_add_u32 s22, s22, 0x100
	s_addc_u32 s23, s23, 0
	s_cmp_lt_u32 s46, 14
	s_cbranch_scc1 .LBB0_985
	s_waitcnt vmcnt(0)
	s_cmpk_gt_u32 s28, 0xff
	s_cbranch_scc1 .LBB0_988
	s_barrier

.LBB0_1099:
	s_lshl_b32 s64, s89, 7
	s_add_u32 s65, s22, s64
	s_addc_u32 s90, s23, 0
	s_add_u32 s62, s65, 0x100
	s_addc_u32 s63, s90, 0
	s_and_b64 s[58:59], s[60:61], exec
	s_cselect_b32 s63, s35, s63
	s_cselect_b32 s62, s84, s62
	s_add_u32 s58, s24, s64
	s_addc_u32 s59, s25, 0
	s_add_u32 s91, s58, 0x100
	s_addc_u32 s92, s59, 0
	s_and_b64 s[58:59], s[60:61], exec
	s_cselect_b32 s59, s29, s92
	s_cselect_b32 s58, s85, s91
	s_add_u32 s64, s26, s64
	s_addc_u32 s91, s27, 0
	s_add_u32 s64, s64, 0x100
	s_addc_u32 s91, s91, 0
	s_and_b64 s[60:61], s[60:61], exec
	s_cselect_b32 s91, s31, s91
	s_cselect_b32 s64, s88, s64
	s_add_i32 s92, 0, 0x10000
	v_add_u32_e32 v154, s92, v19
	s_add_i32 s93, 0, 0x14000
	ds_read_b128 v[158:161], v154
	ds_read_b128 v[162:165], v154 offset:1024
	ds_read_b128 v[166:169], v154 offset:2048
	ds_read_b128 v[170:173], v154 offset:3072
	v_add_u32_e32 v154, s93, v19
	ds_read_b128 v[174:177], v154
	ds_read_b128 v[178:181], v154 offset:1024
	ds_read_b128 v[182:185], v154 offset:2048
	ds_read_b128 v[186:189], v154 offset:3072
	s_add_i32 s94, 0, 0x20000
	s_add_u32 s60, s65, 0x40080
	s_addc_u32 s61, s90, 0
	v_add_u32_e32 v154, 0, v18
	v_add_u32_e32 v155, s94, v156
	v_lshl_add_u64 v[212:213], s[60:61], 0, v[148:149]
	s_add_i32 m0, s71, 0xc000
	ds_read_b128 v[190:193], v154
	ds_read_b128 v[194:197], v154 offset:1024
	ds_read_b128 v[198:201], v154 offset:2048
	ds_read_b128 v[202:205], v154 offset:3072
	ds_read_b128 v[206:209], v154 offset:4096
	ds_read_b128 v[218:221], v154 offset:5120
	ds_read_b128 v[222:225], v154 offset:6144
	ds_read_b128 v[226:229], v154 offset:7168
	ds_read_b128 v[230:233], v155
	ds_read_b128 v[234:237], v155 offset:1024
	global_load_lds_dwordx4 v[212:213], off
	v_lshl_add_u64 v[212:213], s[60:61], 0, v[16:17]
	s_add_i32 m0, s71, 0xe000
	s_nop 0
	global_load_lds_dwordx4 v[212:213], off
	s_waitcnt vmcnt(9) lgkmcnt(0)
	s_setprio 1
	s_barrier
	v_mfma_f32_16x16x32_bf16 v[144:147], v[158:161], v[190:193], v[144:147]
	v_mfma_f32_16x16x32_bf16 v[140:143], v[166:169], v[190:193], v[140:143]
	v_mfma_f32_16x16x32_bf16 v[132:135], v[158:161], v[198:201], v[132:135]
	v_mfma_f32_16x16x32_bf16 v[128:131], v[166:169], v[198:201], v[128:131]
	v_mfma_f32_16x16x32_bf16 v[120:123], v[158:161], v[206:209], v[120:123]
	v_mfma_f32_16x16x32_bf16 v[112:115], v[166:169], v[206:209], v[112:115]
	v_mfma_f32_16x16x32_bf16 v[104:107], v[158:161], v[222:225], v[104:107]
	v_mfma_f32_16x16x32_bf16 v[96:99], v[166:169], v[222:225], v[96:99]
	v_mfma_f32_16x16x32_bf16 v[144:147], v[162:165], v[194:197], v[144:147]
	v_mfma_f32_16x16x32_bf16 v[140:143], v[170:173], v[194:197], v[140:143]
	v_mfma_f32_16x16x32_bf16 v[132:135], v[162:165], v[202:205], v[132:135]
	v_mfma_f32_16x16x32_bf16 v[128:131], v[170:173], v[202:205], v[128:131]
	v_mfma_f32_16x16x32_bf16 v[120:123], v[162:165], v[218:221], v[120:123]
	v_mfma_f32_16x16x32_bf16 v[112:115], v[170:173], v[218:221], v[112:115]
	v_mfma_f32_16x16x32_bf16 v[104:107], v[162:165], v[226:229], v[104:107]
	v_mfma_f32_16x16x32_bf16 v[96:99], v[170:173], v[226:229], v[96:99]
	s_setprio 0
	s_setprio 1
	v_mfma_f32_16x16x32_bf16 v[136:139], v[174:177], v[190:193], v[136:139]
	v_mfma_f32_16x16x32_bf16 v[124:127], v[182:185], v[190:193], v[124:127]
	v_mfma_f32_16x16x32_bf16 v[116:119], v[174:177], v[198:201], v[116:119]
	v_mfma_f32_16x16x32_bf16 v[108:111], v[182:185], v[198:201], v[108:111]
	v_mfma_f32_16x16x32_bf16 v[100:103], v[174:177], v[206:209], v[100:103]
	v_mfma_f32_16x16x32_bf16 v[92:95], v[182:185], v[206:209], v[92:95]
	v_mfma_f32_16x16x32_bf16 v[88:91], v[174:177], v[222:225], v[88:91]
	v_mfma_f32_16x16x32_bf16 v[84:87], v[182:185], v[222:225], v[84:87]
	v_mfma_f32_16x16x32_bf16 v[136:139], v[178:181], v[194:197], v[136:139]
	v_mfma_f32_16x16x32_bf16 v[124:127], v[186:189], v[194:197], v[124:127]
	v_mfma_f32_16x16x32_bf16 v[116:119], v[178:181], v[202:205], v[116:119]
	v_mfma_f32_16x16x32_bf16 v[108:111], v[186:189], v[202:205], v[108:111]
	v_mfma_f32_16x16x32_bf16 v[100:103], v[178:181], v[218:221], v[100:103]
	v_mfma_f32_16x16x32_bf16 v[92:95], v[186:189], v[218:221], v[92:95]
	v_mfma_f32_16x16x32_bf16 v[88:91], v[178:181], v[226:229], v[88:91]
	v_mfma_f32_16x16x32_bf16 v[84:87], v[186:189], v[226:229], v[84:87]
	s_setprio 0
	v_mfma_f32_16x16x32_bf16 v[12:15], v[158:161], v[230:233], v[12:15]
	s_barrier
	v_mfma_f32_16x16x32_bf16 v[4:7], v[174:177], v[230:233], v[4:7]
	v_mfma_f32_16x16x32_bf16 v[8:11], v[166:169], v[230:233], v[8:11]
	v_mfma_f32_16x16x32_bf16 v[0:3], v[182:185], v[230:233], v[0:3]
	v_mfma_f32_16x16x32_bf16 v[12:15], v[162:165], v[234:237], v[12:15]
	v_mfma_f32_16x16x32_bf16 v[4:7], v[178:181], v[234:237], v[4:7]
	v_mfma_f32_16x16x32_bf16 v[8:11], v[170:173], v[234:237], v[8:11]
	v_mfma_f32_16x16x32_bf16 v[0:3], v[186:189], v[234:237], v[0:3]
	s_add_i32 s60, s92, s77
	v_lshl_add_u64 v[212:213], s[58:59], 0, v[148:149]
	s_mov_b32 m0, s60
	ds_read_b128 v[190:193], v154 offset:16384
	ds_read_b128 v[194:197], v154 offset:17408
	ds_read_b128 v[198:201], v154 offset:18432
	ds_read_b128 v[202:205], v154 offset:19456
	ds_read_b128 v[206:209], v154 offset:20480
	ds_read_b128 v[218:221], v154 offset:21504
	ds_read_b128 v[222:225], v154 offset:22528
	ds_read_b128 v[226:229], v154 offset:23552
	global_load_lds_dwordx4 v[212:213], off
	s_add_i32 m0, s60, 0x2000
	s_add_u32 s60, s58, 0x40000
	v_lshl_add_u64 v[238:239], s[58:59], 0, v[16:17]
	s_addc_u32 s61, s59, 0
	s_add_i32 s65, s93, s77
	global_load_lds_dwordx4 v[238:239], off
	v_lshl_add_u64 v[230:231], s[60:61], 0, v[148:149]
	s_mov_b32 m0, s65
	v_lshl_add_u64 v[240:241], s[62:63], 0, v[148:149]
	global_load_lds_dwordx4 v[230:231], off
	v_lshl_add_u64 v[230:231], s[60:61], 0, v[16:17]
	s_add_i32 m0, s65, 0x2000
	s_add_u32 s60, s64, s76
	global_load_lds_dwordx4 v[230:231], off
	s_mov_b32 m0, s71
	v_lshl_add_u64 v[242:243], s[62:63], 0, v[16:17]
	global_load_lds_dwordx4 v[240:241], off
	s_mov_b32 m0, s78
	s_addc_u32 s61, s91, s75
	global_load_lds_dwordx4 v[242:243], off
	v_lshl_add_u64 v[244:245], s[60:61], 0, v[148:149]
	s_add_i32 m0, s94, s79
	s_nop 0
	global_load_lds_dwordx4 v[244:245], off
	s_waitcnt vmcnt(9) lgkmcnt(0)
	s_setprio 1
	s_barrier
	v_mfma_f32_16x16x32_bf16 v[80:83], v[158:161], v[190:193], v[80:83]
	v_mfma_f32_16x16x32_bf16 v[76:79], v[166:169], v[190:193], v[76:79]
	v_mfma_f32_16x16x32_bf16 v[72:75], v[158:161], v[198:201], v[72:75]
	v_mfma_f32_16x16x32_bf16 v[64:67], v[166:169], v[198:201], v[64:67]
	v_mfma_f32_16x16x32_bf16 v[56:59], v[158:161], v[206:209], v[56:59]
	v_mfma_f32_16x16x32_bf16 v[48:51], v[166:169], v[206:209], v[48:51]
	v_mfma_f32_16x16x32_bf16 v[40:43], v[158:161], v[222:225], v[40:43]
	v_mfma_f32_16x16x32_bf16 v[32:35], v[166:169], v[222:225], v[32:35]
	v_mfma_f32_16x16x32_bf16 v[80:83], v[162:165], v[194:197], v[80:83]
	v_mfma_f32_16x16x32_bf16 v[76:79], v[170:173], v[194:197], v[76:79]
	v_mfma_f32_16x16x32_bf16 v[72:75], v[162:165], v[202:205], v[72:75]
	v_mfma_f32_16x16x32_bf16 v[64:67], v[170:173], v[202:205], v[64:67]
	v_mfma_f32_16x16x32_bf16 v[56:59], v[162:165], v[218:221], v[56:59]
	v_mfma_f32_16x16x32_bf16 v[48:51], v[170:173], v[218:221], v[48:51]
	v_mfma_f32_16x16x32_bf16 v[40:43], v[162:165], v[226:229], v[40:43]
	v_mfma_f32_16x16x32_bf16 v[32:35], v[170:173], v[226:229], v[32:35]
	s_setprio 0
	s_setprio 1
	v_mfma_f32_16x16x32_bf16 v[68:71], v[174:177], v[190:193], v[68:71]
	v_mfma_f32_16x16x32_bf16 v[60:63], v[182:185], v[190:193], v[60:63]
	v_mfma_f32_16x16x32_bf16 v[52:55], v[174:177], v[198:201], v[52:55]
	v_mfma_f32_16x16x32_bf16 v[44:47], v[182:185], v[198:201], v[44:47]
	v_mfma_f32_16x16x32_bf16 v[36:39], v[174:177], v[206:209], v[36:39]
	v_mfma_f32_16x16x32_bf16 v[28:31], v[182:185], v[206:209], v[28:31]
	v_mfma_f32_16x16x32_bf16 v[24:27], v[174:177], v[222:225], v[24:27]
	v_mfma_f32_16x16x32_bf16 v[20:23], v[182:185], v[222:225], v[20:23]
	v_mfma_f32_16x16x32_bf16 v[68:71], v[178:181], v[194:197], v[68:71]
	v_mfma_f32_16x16x32_bf16 v[60:63], v[186:189], v[194:197], v[60:63]
	v_mfma_f32_16x16x32_bf16 v[52:55], v[178:181], v[202:205], v[52:55]
	v_mfma_f32_16x16x32_bf16 v[44:47], v[186:189], v[202:205], v[44:47]
	v_mfma_f32_16x16x32_bf16 v[36:39], v[178:181], v[218:221], v[36:39]
	v_mfma_f32_16x16x32_bf16 v[28:31], v[186:189], v[218:221], v[28:31]
	v_mfma_f32_16x16x32_bf16 v[24:27], v[178:181], v[226:229], v[24:27]
	v_mfma_f32_16x16x32_bf16 v[20:23], v[186:189], v[226:229], v[20:23]
	s_barrier
	s_setprio 0
	s_add_i32 s64, 0, 0x18000
	v_add_u32_e32 v155, s64, v19
	s_add_i32 s65, 0, 0x1c000
	ds_read_b128 v[158:161], v155
	ds_read_b128 v[162:165], v155 offset:1024
	ds_read_b128 v[166:169], v155 offset:2048
	ds_read_b128 v[170:173], v155 offset:3072
	v_add_u32_e32 v155, s65, v19
	ds_read_b128 v[174:177], v155
	ds_read_b128 v[178:181], v155 offset:1024
	ds_read_b128 v[182:185], v155 offset:2048
	ds_read_b128 v[186:189], v155 offset:3072
	s_add_i32 s90, 0, 0x21000
	s_add_u32 s60, s62, 0x40000
	s_addc_u32 s61, s63, 0
	s_mov_b32 m0, s80
	v_add_u32_e32 v155, s90, v156
	v_lshl_add_u64 v[246:247], s[60:61], 0, v[148:149]
	ds_read_b128 v[190:193], v154 offset:32768
	ds_read_b128 v[194:197], v154 offset:33792
	ds_read_b128 v[198:201], v154 offset:34816
	ds_read_b128 v[202:205], v154 offset:35840
	ds_read_b128 v[206:209], v154 offset:36864
	ds_read_b128 v[218:221], v154 offset:37888
	ds_read_b128 v[222:225], v154 offset:38912
	ds_read_b128 v[226:229], v154 offset:39936
	ds_read_b128 v[230:233], v155
	ds_read_b128 v[234:237], v155 offset:1024
	global_load_lds_dwordx4 v[246:247], off
	v_lshl_add_u64 v[246:247], s[60:61], 0, v[16:17]
	s_mov_b32 m0, s81
	s_nop 0
	global_load_lds_dwordx4 v[246:247], off
	s_waitcnt vmcnt(9) lgkmcnt(0)
	s_setprio 1
	s_barrier
	v_mfma_f32_16x16x32_bf16 v[144:147], v[158:161], v[190:193], v[144:147]
	v_mfma_f32_16x16x32_bf16 v[140:143], v[166:169], v[190:193], v[140:143]
	v_mfma_f32_16x16x32_bf16 v[132:135], v[158:161], v[198:201], v[132:135]
	v_mfma_f32_16x16x32_bf16 v[128:131], v[166:169], v[198:201], v[128:131]
	v_mfma_f32_16x16x32_bf16 v[120:123], v[158:161], v[206:209], v[120:123]
	v_mfma_f32_16x16x32_bf16 v[112:115], v[166:169], v[206:209], v[112:115]
	v_mfma_f32_16x16x32_bf16 v[104:107], v[158:161], v[222:225], v[104:107]
	v_mfma_f32_16x16x32_bf16 v[96:99], v[166:169], v[222:225], v[96:99]
	v_mfma_f32_16x16x32_bf16 v[144:147], v[162:165], v[194:197], v[144:147]
	v_mfma_f32_16x16x32_bf16 v[140:143], v[170:173], v[194:197], v[140:143]
	v_mfma_f32_16x16x32_bf16 v[132:135], v[162:165], v[202:205], v[132:135]
	v_mfma_f32_16x16x32_bf16 v[128:131], v[170:173], v[202:205], v[128:131]
	v_mfma_f32_16x16x32_bf16 v[120:123], v[162:165], v[218:221], v[120:123]
	v_mfma_f32_16x16x32_bf16 v[112:115], v[170:173], v[218:221], v[112:115]
	v_mfma_f32_16x16x32_bf16 v[104:107], v[162:165], v[226:229], v[104:107]
	v_mfma_f32_16x16x32_bf16 v[96:99], v[170:173], v[226:229], v[96:99]
	s_setprio 0
	s_setprio 1
	v_mfma_f32_16x16x32_bf16 v[136:139], v[174:177], v[190:193], v[136:139]
	v_mfma_f32_16x16x32_bf16 v[124:127], v[182:185], v[190:193], v[124:127]
	v_mfma_f32_16x16x32_bf16 v[116:119], v[174:177], v[198:201], v[116:119]
	v_mfma_f32_16x16x32_bf16 v[108:111], v[182:185], v[198:201], v[108:111]
	v_mfma_f32_16x16x32_bf16 v[100:103], v[174:177], v[206:209], v[100:103]
	v_mfma_f32_16x16x32_bf16 v[92:95], v[182:185], v[206:209], v[92:95]
	v_mfma_f32_16x16x32_bf16 v[88:91], v[174:177], v[222:225], v[88:91]
	v_mfma_f32_16x16x32_bf16 v[84:87], v[182:185], v[222:225], v[84:87]
	v_mfma_f32_16x16x32_bf16 v[136:139], v[178:181], v[194:197], v[136:139]
	v_mfma_f32_16x16x32_bf16 v[124:127], v[186:189], v[194:197], v[124:127]
	v_mfma_f32_16x16x32_bf16 v[116:119], v[178:181], v[202:205], v[116:119]
	v_mfma_f32_16x16x32_bf16 v[108:111], v[186:189], v[202:205], v[108:111]
	v_mfma_f32_16x16x32_bf16 v[100:103], v[178:181], v[218:221], v[100:103]
	v_mfma_f32_16x16x32_bf16 v[92:95], v[186:189], v[218:221], v[92:95]
	v_mfma_f32_16x16x32_bf16 v[88:91], v[178:181], v[226:229], v[88:91]
	v_mfma_f32_16x16x32_bf16 v[84:87], v[186:189], v[226:229], v[84:87]
	s_setprio 0
	v_mfma_f32_16x16x32_bf16 v[12:15], v[158:161], v[230:233], v[12:15]
	s_barrier
	v_mfma_f32_16x16x32_bf16 v[4:7], v[174:177], v[230:233], v[4:7]
	v_mfma_f32_16x16x32_bf16 v[8:11], v[166:169], v[230:233], v[8:11]
	v_mfma_f32_16x16x32_bf16 v[0:3], v[182:185], v[230:233], v[0:3]
	v_mfma_f32_16x16x32_bf16 v[12:15], v[162:165], v[234:237], v[12:15]
	v_mfma_f32_16x16x32_bf16 v[4:7], v[178:181], v[234:237], v[4:7]
	v_mfma_f32_16x16x32_bf16 v[8:11], v[170:173], v[234:237], v[8:11]
	v_mfma_f32_16x16x32_bf16 v[0:3], v[186:189], v[234:237], v[0:3]
	s_add_i32 s60, s64, s77
	v_lshl_add_u64 v[212:213], v[212:213], 0, s[0:1]
	s_mov_b32 m0, s60
	ds_read_b128 v[190:193], v154 offset:49152
	ds_read_b128 v[194:197], v154 offset:50176
	ds_read_b128 v[198:201], v154 offset:51200
	ds_read_b128 v[202:205], v154 offset:52224
	ds_read_b128 v[206:209], v154 offset:53248
	ds_read_b128 v[218:221], v154 offset:54272
	ds_read_b128 v[222:225], v154 offset:55296
	ds_read_b128 v[226:229], v154 offset:56320
	global_load_lds_dwordx4 v[212:213], off
	s_add_i32 m0, s60, 0x2000
	s_add_u32 s58, s58, 0x40080
	v_lshl_add_u64 v[212:213], v[238:239], 0, s[0:1]
	s_addc_u32 s59, s59, 0
	s_add_i32 s60, s65, s77
	global_load_lds_dwordx4 v[212:213], off
	v_lshl_add_u64 v[212:213], s[58:59], 0, v[148:149]
	s_mov_b32 m0, s60
	s_nop 0
	global_load_lds_dwordx4 v[212:213], off
	v_lshl_add_u64 v[212:213], s[58:59], 0, v[16:17]
	s_add_i32 m0, s60, 0x2000
	s_nop 0
	global_load_lds_dwordx4 v[212:213], off
	v_lshl_add_u64 v[212:213], v[240:241], 0, s[0:1]
	s_mov_b32 m0, s5
	s_nop 0
	global_load_lds_dwordx4 v[212:213], off
	v_lshl_add_u64 v[212:213], v[242:243], 0, s[0:1]
	s_mov_b32 m0, s82
	s_nop 0
	global_load_lds_dwordx4 v[212:213], off
	v_lshl_add_u64 v[212:213], v[244:245], 0, s[0:1]
	s_add_i32 m0, s90, s79
	s_nop 0
	global_load_lds_dwordx4 v[212:213], off
	s_waitcnt vmcnt(9) lgkmcnt(0)
	s_setprio 1
	s_barrier
	v_mfma_f32_16x16x32_bf16 v[80:83], v[158:161], v[190:193], v[80:83]
	v_mfma_f32_16x16x32_bf16 v[76:79], v[166:169], v[190:193], v[76:79]
	v_mfma_f32_16x16x32_bf16 v[72:75], v[158:161], v[198:201], v[72:75]
	v_mfma_f32_16x16x32_bf16 v[64:67], v[166:169], v[198:201], v[64:67]
	v_mfma_f32_16x16x32_bf16 v[56:59], v[158:161], v[206:209], v[56:59]
	v_mfma_f32_16x16x32_bf16 v[48:51], v[166:169], v[206:209], v[48:51]
	v_mfma_f32_16x16x32_bf16 v[40:43], v[158:161], v[222:225], v[40:43]
	v_mfma_f32_16x16x32_bf16 v[32:35], v[166:169], v[222:225], v[32:35]
	v_mfma_f32_16x16x32_bf16 v[80:83], v[162:165], v[194:197], v[80:83]
	v_mfma_f32_16x16x32_bf16 v[76:79], v[170:173], v[194:197], v[76:79]
	v_mfma_f32_16x16x32_bf16 v[72:75], v[162:165], v[202:205], v[72:75]
	v_mfma_f32_16x16x32_bf16 v[64:67], v[170:173], v[202:205], v[64:67]
	v_mfma_f32_16x16x32_bf16 v[56:59], v[162:165], v[218:221], v[56:59]
	v_mfma_f32_16x16x32_bf16 v[48:51], v[170:173], v[218:221], v[48:51]
	v_mfma_f32_16x16x32_bf16 v[40:43], v[162:165], v[226:229], v[40:43]
	v_mfma_f32_16x16x32_bf16 v[32:35], v[170:173], v[226:229], v[32:35]
	s_setprio 0
	s_setprio 1
	v_mfma_f32_16x16x32_bf16 v[68:71], v[174:177], v[190:193], v[68:71]
	v_mfma_f32_16x16x32_bf16 v[60:63], v[182:185], v[190:193], v[60:63]
	v_mfma_f32_16x16x32_bf16 v[52:55], v[174:177], v[198:201], v[52:55]
	v_mfma_f32_16x16x32_bf16 v[44:47], v[182:185], v[198:201], v[44:47]
	v_mfma_f32_16x16x32_bf16 v[36:39], v[174:177], v[206:209], v[36:39]
	v_mfma_f32_16x16x32_bf16 v[28:31], v[182:185], v[206:209], v[28:31]
	v_mfma_f32_16x16x32_bf16 v[24:27], v[174:177], v[222:225], v[24:27]
	v_mfma_f32_16x16x32_bf16 v[20:23], v[182:185], v[222:225], v[20:23]
	v_mfma_f32_16x16x32_bf16 v[68:71], v[178:181], v[194:197], v[68:71]
	v_mfma_f32_16x16x32_bf16 v[60:63], v[186:189], v[194:197], v[60:63]
	v_mfma_f32_16x16x32_bf16 v[52:55], v[178:181], v[202:205], v[52:55]
	v_mfma_f32_16x16x32_bf16 v[44:47], v[186:189], v[202:205], v[44:47]
	v_mfma_f32_16x16x32_bf16 v[36:39], v[178:181], v[218:221], v[36:39]
	v_mfma_f32_16x16x32_bf16 v[28:31], v[186:189], v[218:221], v[28:31]
	v_mfma_f32_16x16x32_bf16 v[24:27], v[178:181], v[226:229], v[24:27]
	v_mfma_f32_16x16x32_bf16 v[20:23], v[186:189], v[226:229], v[20:23]
	s_barrier
	s_setprio 0
	s_add_i32 s58, s89, 2
	s_cmp_gt_u32 s89, 13
	s_cbranch_scc1 .LBB0_1101
	s_mov_b32 s89, s58
	s_branch .LBB0_1085
